# next-h stores of norm0 / norm2 (read back only by the FFN-in tiles of the same block, same XCD) as plain L2 write-back stores; norm1's h stays write-through (the gMLP tiles read it from other XCDs)
# baseline (speedup 1.0000x reference)
.Lnw_skip_n0g:
	s_or_b64 exec, exec, s[40:41]
	s_waitcnt vmcnt(36)
	s_barrier
	global_load_dwordx2 v[86:87], v1, s[58:59] offset:0
	global_load_dwordx2 v[90:91], v1, s[58:59] offset:512
	global_load_dwordx2 v[94:95], v1, s[58:59] offset:1024
	global_load_dwordx2 v[98:99], v1, s[58:59] offset:1536
	global_load_dwordx2 v[88:89], v1, s[60:61] offset:0
	global_load_dwordx2 v[92:93], v1, s[60:61] offset:512
	global_load_dwordx2 v[96:97], v1, s[60:61] offset:1024
	global_load_dwordx2 v[100:101], v1, s[60:61] offset:1536
	s_add_u32 s58, s58, 0x800
	s_addc_u32 s59, s59, 0
	s_add_u32 s60, s60, 0x800
	s_addc_u32 s61, s61, 0
	global_load_dwordx2 v[118:119], v1, s[58:59] offset:0
	global_load_dwordx2 v[122:123], v1, s[58:59] offset:512
	global_load_dwordx2 v[134:135], v1, s[58:59] offset:1024
	global_load_dwordx2 v[138:139], v1, s[58:59] offset:1536
	global_load_dwordx2 v[120:121], v1, s[60:61] offset:0
	global_load_dwordx2 v[124:125], v1, s[60:61] offset:512
	global_load_dwordx2 v[136:137], v1, s[60:61] offset:1024
	global_load_dwordx2 v[140:141], v1, s[60:61] offset:1536
	s_add_u32 s58, s58, 0x800
	s_addc_u32 s59, s59, 0
	s_add_u32 s60, s60, 0x800
	s_addc_u32 s61, s61, 0
	global_load_dwordx2 v[172:173], v1, s[58:59] offset:0
	global_load_dwordx2 v[176:177], v1, s[58:59] offset:512
	global_load_dwordx2 v[204:205], v1, s[58:59] offset:1024
	global_load_dwordx2 v[214:215], v1, s[58:59] offset:1536
	global_load_dwordx2 v[174:175], v1, s[60:61] offset:0
	global_load_dwordx2 v[178:179], v1, s[60:61] offset:512
	global_load_dwordx2 v[206:207], v1, s[60:61] offset:1024
	global_load_dwordx2 v[216:217], v1, s[60:61] offset:1536
	s_add_u32 s58, s58, 0x800
	s_addc_u32 s59, s59, 0
	s_add_u32 s60, s60, 0x800
	s_addc_u32 s61, s61, 0
	global_load_dwordx2 v[234:235], v1, s[58:59] offset:0
	global_load_dwordx2 v[238:239], v1, s[58:59] offset:512
	global_load_dwordx2 v[242:243], v1, s[58:59] offset:1024
	global_load_dwordx2 v[246:247], v1, s[58:59] offset:1536
	global_load_dwordx2 v[236:237], v1, s[60:61] offset:0
	global_load_dwordx2 v[240:241], v1, s[60:61] offset:512
	global_load_dwordx2 v[244:245], v1, s[60:61] offset:1024
	global_load_dwordx2 v[248:249], v1, s[60:61] offset:1536
	s_add_u32 s58, s58, 0x800
	s_addc_u32 s59, s59, 0
	s_add_u32 s60, s60, 0x800
	s_addc_u32 s61, s61, 0
	s_waitcnt vmcnt(24)
	v_lshlrev_b32_e32 v14, 16, v86
	v_and_b32_e32 v15, 0xffff0000, v86
	v_lshlrev_b32_e32 v16, 16, v88
	v_and_b32_e32 v17, 0xffff0000, v88
	v_lshlrev_b32_e32 v18, 16, v87
	v_and_b32_e32 v19, 0xffff0000, v87
	v_lshlrev_b32_e32 v20, 16, v89
	v_and_b32_e32 v21, 0xffff0000, v89
	v_pk_add_f32 v[86:87], v[14:15], v[16:17]
	v_pk_add_f32 v[88:89], v[18:19], v[20:21]
	v_lshlrev_b32_e32 v14, 16, v90
	v_and_b32_e32 v15, 0xffff0000, v90
	v_lshlrev_b32_e32 v16, 16, v92
	v_and_b32_e32 v17, 0xffff0000, v92
	v_lshlrev_b32_e32 v18, 16, v91
	v_and_b32_e32 v19, 0xffff0000, v91
	v_lshlrev_b32_e32 v20, 16, v93
	v_and_b32_e32 v21, 0xffff0000, v93
	v_pk_add_f32 v[90:91], v[14:15], v[16:17]
	v_pk_add_f32 v[92:93], v[18:19], v[20:21]
	v_lshlrev_b32_e32 v14, 16, v94
	v_and_b32_e32 v15, 0xffff0000, v94
	v_lshlrev_b32_e32 v16, 16, v96
	v_and_b32_e32 v17, 0xffff0000, v96
	v_lshlrev_b32_e32 v18, 16, v95
	v_and_b32_e32 v19, 0xffff0000, v95
	v_lshlrev_b32_e32 v20, 16, v97
	v_and_b32_e32 v21, 0xffff0000, v97
	v_pk_add_f32 v[94:95], v[14:15], v[16:17]
	v_pk_add_f32 v[96:97], v[18:19], v[20:21]
	v_lshlrev_b32_e32 v14, 16, v98
	v_and_b32_e32 v15, 0xffff0000, v98
	v_lshlrev_b32_e32 v16, 16, v100
	v_and_b32_e32 v17, 0xffff0000, v100
	v_lshlrev_b32_e32 v18, 16, v99
	v_and_b32_e32 v19, 0xffff0000, v99
	v_lshlrev_b32_e32 v20, 16, v101
	v_and_b32_e32 v21, 0xffff0000, v101
	v_pk_add_f32 v[98:99], v[14:15], v[16:17]
	v_pk_add_f32 v[100:101], v[18:19], v[20:21]
	v_pk_mul_f32 v[12:13], v[86:87], v[86:87]
	v_pk_fma_f32 v[12:13], v[88:89], v[88:89], v[12:13]
	v_pk_fma_f32 v[12:13], v[90:91], v[90:91], v[12:13]
	v_pk_fma_f32 v[12:13], v[92:93], v[92:93], v[12:13]
	v_pk_fma_f32 v[12:13], v[94:95], v[94:95], v[12:13]
	v_pk_fma_f32 v[12:13], v[96:97], v[96:97], v[12:13]
	v_pk_fma_f32 v[12:13], v[98:99], v[98:99], v[12:13]
	v_pk_fma_f32 v[12:13], v[100:101], v[100:101], v[12:13]
	v_add_f32_e32 v5, v12, v13
	s_nop 1
	v_add_f32_dpp v5, v5, v5 quad_perm:[1,0,3,2] row_mask:0xf bank_mask:0xf
	s_nop 1
	v_add_f32_dpp v5, v5, v5 quad_perm:[2,3,0,1] row_mask:0xf bank_mask:0xf
	s_nop 1
	v_add_f32_dpp v5, v5, v5 row_half_mirror row_mask:0xf bank_mask:0xf
	s_nop 1
	v_add_f32_dpp v5, v5, v5 row_mirror row_mask:0xf bank_mask:0xf
	s_nop 1
	v_add_f32_dpp v5, v5, v5 row_bcast:15 row_mask:0xa bank_mask:0xf
	s_nop 1
	v_add_f32_dpp v5, v5, v5 row_bcast:31 row_mask:0xc bank_mask:0xf
	s_nop 1
	v_readlane_b32 s32, v5, 63
	s_nop 1
	v_mov_b32_e32 v6, s32
	v_fmamk_f32 v6, v6, 0x3a800000, v146
	v_rsq_f32_e32 v6, v6
	s_nop 0
	v_mul_f32_e32 v8, 0.5, v6
	v_pk_mul_f32 v[14:15], v[86:87], v[8:9] op_sel_hi:[1,0]
	v_pk_fma_f32 v[70:71], v[22:23], v[14:15], v[70:71]
	v_pk_mul_f32 v[14:15], v[88:89], v[8:9] op_sel_hi:[1,0]
	v_pk_fma_f32 v[72:73], v[24:25], v[14:15], v[72:73]
	v_pk_mul_f32 v[14:15], v[90:91], v[8:9] op_sel_hi:[1,0]
	v_pk_fma_f32 v[74:75], v[26:27], v[14:15], v[74:75]
	v_pk_mul_f32 v[14:15], v[92:93], v[8:9] op_sel_hi:[1,0]
	v_pk_fma_f32 v[76:77], v[28:29], v[14:15], v[76:77]
	v_pk_mul_f32 v[14:15], v[94:95], v[8:9] op_sel_hi:[1,0]
	v_pk_fma_f32 v[78:79], v[30:31], v[14:15], v[78:79]
	v_pk_mul_f32 v[14:15], v[96:97], v[8:9] op_sel_hi:[1,0]
	v_pk_fma_f32 v[80:81], v[32:33], v[14:15], v[80:81]
	v_pk_mul_f32 v[14:15], v[98:99], v[8:9] op_sel_hi:[1,0]
	v_pk_fma_f32 v[82:83], v[34:35], v[14:15], v[82:83]
	v_pk_mul_f32 v[14:15], v[100:101], v[8:9] op_sel_hi:[1,0]
	v_pk_fma_f32 v[84:85], v[36:37], v[14:15], v[84:85]
	v_pk_mul_f32 v[12:13], v[70:71], v[70:71]
	v_pk_fma_f32 v[12:13], v[72:73], v[72:73], v[12:13]
	v_pk_fma_f32 v[12:13], v[74:75], v[74:75], v[12:13]
	v_pk_fma_f32 v[12:13], v[76:77], v[76:77], v[12:13]
	v_pk_fma_f32 v[12:13], v[78:79], v[78:79], v[12:13]
	v_pk_fma_f32 v[12:13], v[80:81], v[80:81], v[12:13]
	v_pk_fma_f32 v[12:13], v[82:83], v[82:83], v[12:13]
	v_pk_fma_f32 v[12:13], v[84:85], v[84:85], v[12:13]
	v_add_f32_e32 v5, v12, v13
	s_nop 1
	v_add_f32_dpp v5, v5, v5 quad_perm:[1,0,3,2] row_mask:0xf bank_mask:0xf
	s_nop 1
	v_add_f32_dpp v5, v5, v5 quad_perm:[2,3,0,1] row_mask:0xf bank_mask:0xf
	s_nop 1
	v_add_f32_dpp v5, v5, v5 row_half_mirror row_mask:0xf bank_mask:0xf
	s_nop 1
	v_add_f32_dpp v5, v5, v5 row_mirror row_mask:0xf bank_mask:0xf
	s_nop 1
	v_add_f32_dpp v5, v5, v5 row_bcast:15 row_mask:0xa bank_mask:0xf
	s_nop 1
	v_add_f32_dpp v5, v5, v5 row_bcast:31 row_mask:0xc bank_mask:0xf
	s_nop 1
	v_readlane_b32 s32, v5, 63
	s_nop 1
	v_mov_b32_e32 v6, s32
	v_fmamk_f32 v6, v6, 0x3a800000, v146
	v_rsq_f32_e32 v6, v6
	s_nop 0
	v_mov_b32_e32 v10, v6
	v_pk_mul_f32 v[14:15], v[70:71], v[10:11] op_sel_hi:[1,0]
	v_pk_fma_f32 v[16:17], v[54:55], v[14:15], v[38:39]
	v_pk_mul_f32 v[14:15], v[72:73], v[10:11] op_sel_hi:[1,0]
	v_pk_fma_f32 v[18:19], v[56:57], v[14:15], v[40:41]
	v_cvt_pk_bf16_f32 v86, v16, v17
	v_cvt_pk_bf16_f32 v87, v18, v19
	v_pk_mul_f32 v[14:15], v[74:75], v[10:11] op_sel_hi:[1,0]
	v_pk_fma_f32 v[16:17], v[58:59], v[14:15], v[42:43]
	v_pk_mul_f32 v[14:15], v[76:77], v[10:11] op_sel_hi:[1,0]
	v_pk_fma_f32 v[18:19], v[60:61], v[14:15], v[44:45]
	v_cvt_pk_bf16_f32 v90, v16, v17
	v_cvt_pk_bf16_f32 v91, v18, v19
	v_pk_mul_f32 v[14:15], v[78:79], v[10:11] op_sel_hi:[1,0]
	v_pk_fma_f32 v[16:17], v[62:63], v[14:15], v[46:47]
	v_pk_mul_f32 v[14:15], v[80:81], v[10:11] op_sel_hi:[1,0]
	v_pk_fma_f32 v[18:19], v[64:65], v[14:15], v[48:49]
	v_cvt_pk_bf16_f32 v94, v16, v17
	v_cvt_pk_bf16_f32 v95, v18, v19
	v_pk_mul_f32 v[14:15], v[82:83], v[10:11] op_sel_hi:[1,0]
	v_pk_fma_f32 v[16:17], v[66:67], v[14:15], v[50:51]
	v_pk_mul_f32 v[14:15], v[84:85], v[10:11] op_sel_hi:[1,0]
	v_pk_fma_f32 v[18:19], v[68:69], v[14:15], v[52:53]
	v_cvt_pk_bf16_f32 v98, v16, v17
	v_cvt_pk_bf16_f32 v99, v18, v19
	global_store_dwordx2 v1, v[86:87], s[62:63] offset:0
	global_store_dwordx2 v1, v[90:91], s[62:63] offset:512
	global_store_dwordx2 v1, v[94:95], s[62:63] offset:1024
	global_store_dwordx2 v1, v[98:99], s[62:63] offset:1536
	global_store_dwordx4 v0, v[70:73], s[46:47] offset:0
	global_store_dwordx4 v0, v[74:77], s[46:47] offset:1024
	global_store_dwordx4 v0, v[78:81], s[46:47] offset:2048
	global_store_dwordx4 v0, v[82:85], s[46:47] offset:3072
	s_add_u32 s46, s46, 0x1000
	s_addc_u32 s47, s47, 0
	s_add_u32 s62, s62, 0x800
	s_addc_u32 s63, s63, 0
	s_waitcnt vmcnt(24)
	v_lshlrev_b32_e32 v14, 16, v118
	v_and_b32_e32 v15, 0xffff0000, v118
	v_lshlrev_b32_e32 v16, 16, v120
	v_and_b32_e32 v17, 0xffff0000, v120
	v_lshlrev_b32_e32 v18, 16, v119
	v_and_b32_e32 v19, 0xffff0000, v119
	v_lshlrev_b32_e32 v20, 16, v121
	v_and_b32_e32 v21, 0xffff0000, v121
	v_pk_add_f32 v[118:119], v[14:15], v[16:17]
	v_pk_add_f32 v[120:121], v[18:19], v[20:21]
	v_lshlrev_b32_e32 v14, 16, v122
	v_and_b32_e32 v15, 0xffff0000, v122
	v_lshlrev_b32_e32 v16, 16, v124
	v_and_b32_e32 v17, 0xffff0000, v124
	v_lshlrev_b32_e32 v18, 16, v123
	v_and_b32_e32 v19, 0xffff0000, v123
	v_lshlrev_b32_e32 v20, 16, v125
	v_and_b32_e32 v21, 0xffff0000, v125
	v_pk_add_f32 v[122:123], v[14:15], v[16:17]
	v_pk_add_f32 v[124:125], v[18:19], v[20:21]
	v_lshlrev_b32_e32 v14, 16, v134
	v_and_b32_e32 v15, 0xffff0000, v134
	v_lshlrev_b32_e32 v16, 16, v136
	v_and_b32_e32 v17, 0xffff0000, v136
	v_lshlrev_b32_e32 v18, 16, v135
	v_and_b32_e32 v19, 0xffff0000, v135
	v_lshlrev_b32_e32 v20, 16, v137
	v_and_b32_e32 v21, 0xffff0000, v137
	v_pk_add_f32 v[134:135], v[14:15], v[16:17]
	v_pk_add_f32 v[136:137], v[18:19], v[20:21]
	v_lshlrev_b32_e32 v14, 16, v138
	v_and_b32_e32 v15, 0xffff0000, v138
	v_lshlrev_b32_e32 v16, 16, v140
	v_and_b32_e32 v17, 0xffff0000, v140
	v_lshlrev_b32_e32 v18, 16, v139
	v_and_b32_e32 v19, 0xffff0000, v139
	v_lshlrev_b32_e32 v20, 16, v141
	v_and_b32_e32 v21, 0xffff0000, v141
	v_pk_add_f32 v[138:139], v[14:15], v[16:17]
	v_pk_add_f32 v[140:141], v[18:19], v[20:21]
	v_pk_mul_f32 v[12:13], v[118:119], v[118:119]
	v_pk_fma_f32 v[12:13], v[120:121], v[120:121], v[12:13]
	v_pk_fma_f32 v[12:13], v[122:123], v[122:123], v[12:13]
	v_pk_fma_f32 v[12:13], v[124:125], v[124:125], v[12:13]
	v_pk_fma_f32 v[12:13], v[134:135], v[134:135], v[12:13]
	v_pk_fma_f32 v[12:13], v[136:137], v[136:137], v[12:13]
	v_pk_fma_f32 v[12:13], v[138:139], v[138:139], v[12:13]
	v_pk_fma_f32 v[12:13], v[140:141], v[140:141], v[12:13]
	v_add_f32_e32 v5, v12, v13
	s_nop 1
	v_add_f32_dpp v5, v5, v5 quad_perm:[1,0,3,2] row_mask:0xf bank_mask:0xf
	s_nop 1
	v_add_f32_dpp v5, v5, v5 quad_perm:[2,3,0,1] row_mask:0xf bank_mask:0xf
	s_nop 1
	v_add_f32_dpp v5, v5, v5 row_half_mirror row_mask:0xf bank_mask:0xf
	s_nop 1
	v_add_f32_dpp v5, v5, v5 row_mirror row_mask:0xf bank_mask:0xf
	s_nop 1
	v_add_f32_dpp v5, v5, v5 row_bcast:15 row_mask:0xa bank_mask:0xf
	s_nop 1
	v_add_f32_dpp v5, v5, v5 row_bcast:31 row_mask:0xc bank_mask:0xf
	s_nop 1
	v_readlane_b32 s32, v5, 63
	s_nop 1
	v_mov_b32_e32 v6, s32
	v_fmamk_f32 v6, v6, 0x3a800000, v146
	v_rsq_f32_e32 v6, v6
	s_nop 0
	v_mul_f32_e32 v8, 0.5, v6
	v_pk_mul_f32 v[14:15], v[118:119], v[8:9] op_sel_hi:[1,0]
	v_pk_fma_f32 v[102:103], v[22:23], v[14:15], v[102:103]
	v_pk_mul_f32 v[14:15], v[120:121], v[8:9] op_sel_hi:[1,0]
	v_pk_fma_f32 v[104:105], v[24:25], v[14:15], v[104:105]
	v_pk_mul_f32 v[14:15], v[122:123], v[8:9] op_sel_hi:[1,0]
	v_pk_fma_f32 v[106:107], v[26:27], v[14:15], v[106:107]
	v_pk_mul_f32 v[14:15], v[124:125], v[8:9] op_sel_hi:[1,0]
	v_pk_fma_f32 v[108:109], v[28:29], v[14:15], v[108:109]
	v_pk_mul_f32 v[14:15], v[134:135], v[8:9] op_sel_hi:[1,0]
	v_pk_fma_f32 v[110:111], v[30:31], v[14:15], v[110:111]
	v_pk_mul_f32 v[14:15], v[136:137], v[8:9] op_sel_hi:[1,0]
	v_pk_fma_f32 v[112:113], v[32:33], v[14:15], v[112:113]
	v_pk_mul_f32 v[14:15], v[138:139], v[8:9] op_sel_hi:[1,0]
	v_pk_fma_f32 v[114:115], v[34:35], v[14:15], v[114:115]
	v_pk_mul_f32 v[14:15], v[140:141], v[8:9] op_sel_hi:[1,0]
	v_pk_fma_f32 v[116:117], v[36:37], v[14:15], v[116:117]
	v_pk_mul_f32 v[12:13], v[102:103], v[102:103]
	v_pk_fma_f32 v[12:13], v[104:105], v[104:105], v[12:13]
	v_pk_fma_f32 v[12:13], v[106:107], v[106:107], v[12:13]
	v_pk_fma_f32 v[12:13], v[108:109], v[108:109], v[12:13]
	v_pk_fma_f32 v[12:13], v[110:111], v[110:111], v[12:13]
	v_pk_fma_f32 v[12:13], v[112:113], v[112:113], v[12:13]
	v_pk_fma_f32 v[12:13], v[114:115], v[114:115], v[12:13]
	v_pk_fma_f32 v[12:13], v[116:117], v[116:117], v[12:13]
	v_add_f32_e32 v5, v12, v13
	s_nop 1
	v_add_f32_dpp v5, v5, v5 quad_perm:[1,0,3,2] row_mask:0xf bank_mask:0xf
	s_nop 1
	v_add_f32_dpp v5, v5, v5 quad_perm:[2,3,0,1] row_mask:0xf bank_mask:0xf
	s_nop 1
	v_add_f32_dpp v5, v5, v5 row_half_mirror row_mask:0xf bank_mask:0xf
	s_nop 1
	v_add_f32_dpp v5, v5, v5 row_mirror row_mask:0xf bank_mask:0xf
	s_nop 1
	v_add_f32_dpp v5, v5, v5 row_bcast:15 row_mask:0xa bank_mask:0xf
	s_nop 1
	v_add_f32_dpp v5, v5, v5 row_bcast:31 row_mask:0xc bank_mask:0xf
	s_nop 1
	v_readlane_b32 s32, v5, 63
	s_nop 1
	v_mov_b32_e32 v6, s32
	v_fmamk_f32 v6, v6, 0x3a800000, v146
	v_rsq_f32_e32 v6, v6
	s_nop 0
	v_mov_b32_e32 v10, v6
	v_pk_mul_f32 v[14:15], v[102:103], v[10:11] op_sel_hi:[1,0]
	v_pk_fma_f32 v[16:17], v[54:55], v[14:15], v[38:39]
	v_pk_mul_f32 v[14:15], v[104:105], v[10:11] op_sel_hi:[1,0]
	v_pk_fma_f32 v[18:19], v[56:57], v[14:15], v[40:41]
	v_cvt_pk_bf16_f32 v118, v16, v17
	v_cvt_pk_bf16_f32 v119, v18, v19
	v_pk_mul_f32 v[14:15], v[106:107], v[10:11] op_sel_hi:[1,0]
	v_pk_fma_f32 v[16:17], v[58:59], v[14:15], v[42:43]
	v_pk_mul_f32 v[14:15], v[108:109], v[10:11] op_sel_hi:[1,0]
	v_pk_fma_f32 v[18:19], v[60:61], v[14:15], v[44:45]
	v_cvt_pk_bf16_f32 v122, v16, v17
	v_cvt_pk_bf16_f32 v123, v18, v19
	v_pk_mul_f32 v[14:15], v[110:111], v[10:11] op_sel_hi:[1,0]
	v_pk_fma_f32 v[16:17], v[62:63], v[14:15], v[46:47]
	v_pk_mul_f32 v[14:15], v[112:113], v[10:11] op_sel_hi:[1,0]
	v_pk_fma_f32 v[18:19], v[64:65], v[14:15], v[48:49]
	v_cvt_pk_bf16_f32 v134, v16, v17
	v_cvt_pk_bf16_f32 v135, v18, v19
	v_pk_mul_f32 v[14:15], v[114:115], v[10:11] op_sel_hi:[1,0]
	v_pk_fma_f32 v[16:17], v[66:67], v[14:15], v[50:51]
	v_pk_mul_f32 v[14:15], v[116:117], v[10:11] op_sel_hi:[1,0]
	v_pk_fma_f32 v[18:19], v[68:69], v[14:15], v[52:53]
	v_cvt_pk_bf16_f32 v138, v16, v17
	v_cvt_pk_bf16_f32 v139, v18, v19
	global_store_dwordx2 v1, v[118:119], s[62:63] offset:0
	global_store_dwordx2 v1, v[122:123], s[62:63] offset:512
	global_store_dwordx2 v1, v[134:135], s[62:63] offset:1024
	global_store_dwordx2 v1, v[138:139], s[62:63] offset:1536
	global_store_dwordx4 v0, v[102:105], s[46:47] offset:0
	global_store_dwordx4 v0, v[106:109], s[46:47] offset:1024
	global_store_dwordx4 v0, v[110:113], s[46:47] offset:2048
	global_store_dwordx4 v0, v[114:117], s[46:47] offset:3072
	s_add_u32 s46, s46, 0x1000
	s_addc_u32 s47, s47, 0
	s_add_u32 s62, s62, 0x800
	s_addc_u32 s63, s63, 0
	s_waitcnt vmcnt(24)
	v_lshlrev_b32_e32 v14, 16, v172
	v_and_b32_e32 v15, 0xffff0000, v172
	v_lshlrev_b32_e32 v16, 16, v174
	v_and_b32_e32 v17, 0xffff0000, v174
	v_lshlrev_b32_e32 v18, 16, v173
	v_and_b32_e32 v19, 0xffff0000, v173
	v_lshlrev_b32_e32 v20, 16, v175
	v_and_b32_e32 v21, 0xffff0000, v175
	v_pk_add_f32 v[172:173], v[14:15], v[16:17]
	v_pk_add_f32 v[174:175], v[18:19], v[20:21]
	v_lshlrev_b32_e32 v14, 16, v176
	v_and_b32_e32 v15, 0xffff0000, v176
	v_lshlrev_b32_e32 v16, 16, v178
	v_and_b32_e32 v17, 0xffff0000, v178
	v_lshlrev_b32_e32 v18, 16, v177
	v_and_b32_e32 v19, 0xffff0000, v177
	v_lshlrev_b32_e32 v20, 16, v179
	v_and_b32_e32 v21, 0xffff0000, v179
	v_pk_add_f32 v[176:177], v[14:15], v[16:17]
	v_pk_add_f32 v[178:179], v[18:19], v[20:21]
	v_lshlrev_b32_e32 v14, 16, v204
	v_and_b32_e32 v15, 0xffff0000, v204
	v_lshlrev_b32_e32 v16, 16, v206
	v_and_b32_e32 v17, 0xffff0000, v206
	v_lshlrev_b32_e32 v18, 16, v205
	v_and_b32_e32 v19, 0xffff0000, v205
	v_lshlrev_b32_e32 v20, 16, v207
	v_and_b32_e32 v21, 0xffff0000, v207
	v_pk_add_f32 v[204:205], v[14:15], v[16:17]
	v_pk_add_f32 v[206:207], v[18:19], v[20:21]
	v_lshlrev_b32_e32 v14, 16, v214
	v_and_b32_e32 v15, 0xffff0000, v214
	v_lshlrev_b32_e32 v16, 16, v216
	v_and_b32_e32 v17, 0xffff0000, v216
	v_lshlrev_b32_e32 v18, 16, v215
	v_and_b32_e32 v19, 0xffff0000, v215
	v_lshlrev_b32_e32 v20, 16, v217
	v_and_b32_e32 v21, 0xffff0000, v217
	v_pk_add_f32 v[214:215], v[14:15], v[16:17]
	v_pk_add_f32 v[216:217], v[18:19], v[20:21]
	v_pk_mul_f32 v[12:13], v[172:173], v[172:173]
	v_pk_fma_f32 v[12:13], v[174:175], v[174:175], v[12:13]
	v_pk_fma_f32 v[12:13], v[176:177], v[176:177], v[12:13]
	v_pk_fma_f32 v[12:13], v[178:179], v[178:179], v[12:13]
	v_pk_fma_f32 v[12:13], v[204:205], v[204:205], v[12:13]
	v_pk_fma_f32 v[12:13], v[206:207], v[206:207], v[12:13]
	v_pk_fma_f32 v[12:13], v[214:215], v[214:215], v[12:13]
	v_pk_fma_f32 v[12:13], v[216:217], v[216:217], v[12:13]
	v_add_f32_e32 v5, v12, v13
	s_nop 1
	v_add_f32_dpp v5, v5, v5 quad_perm:[1,0,3,2] row_mask:0xf bank_mask:0xf
	s_nop 1
	v_add_f32_dpp v5, v5, v5 quad_perm:[2,3,0,1] row_mask:0xf bank_mask:0xf
	s_nop 1
	v_add_f32_dpp v5, v5, v5 row_half_mirror row_mask:0xf bank_mask:0xf
	s_nop 1
	v_add_f32_dpp v5, v5, v5 row_mirror row_mask:0xf bank_mask:0xf
	s_nop 1
	v_add_f32_dpp v5, v5, v5 row_bcast:15 row_mask:0xa bank_mask:0xf
	s_nop 1
	v_add_f32_dpp v5, v5, v5 row_bcast:31 row_mask:0xc bank_mask:0xf
	s_nop 1
	v_readlane_b32 s32, v5, 63
	s_nop 1
	v_mov_b32_e32 v6, s32
	v_fmamk_f32 v6, v6, 0x3a800000, v146
	v_rsq_f32_e32 v6, v6
	s_nop 0
	v_mul_f32_e32 v8, 0.5, v6
	v_pk_mul_f32 v[14:15], v[172:173], v[8:9] op_sel_hi:[1,0]
	v_pk_fma_f32 v[154:155], v[22:23], v[14:15], v[154:155]
	v_pk_mul_f32 v[14:15], v[174:175], v[8:9] op_sel_hi:[1,0]
	v_pk_fma_f32 v[156:157], v[24:25], v[14:15], v[156:157]
	v_pk_mul_f32 v[14:15], v[176:177], v[8:9] op_sel_hi:[1,0]
	v_pk_fma_f32 v[158:159], v[26:27], v[14:15], v[158:159]
	v_pk_mul_f32 v[14:15], v[178:179], v[8:9] op_sel_hi:[1,0]
	v_pk_fma_f32 v[160:161], v[28:29], v[14:15], v[160:161]
	v_pk_mul_f32 v[14:15], v[204:205], v[8:9] op_sel_hi:[1,0]
	v_pk_fma_f32 v[162:163], v[30:31], v[14:15], v[162:163]
	v_pk_mul_f32 v[14:15], v[206:207], v[8:9] op_sel_hi:[1,0]
	v_pk_fma_f32 v[164:165], v[32:33], v[14:15], v[164:165]
	v_pk_mul_f32 v[14:15], v[214:215], v[8:9] op_sel_hi:[1,0]
	v_pk_fma_f32 v[168:169], v[34:35], v[14:15], v[168:169]
	v_pk_mul_f32 v[14:15], v[216:217], v[8:9] op_sel_hi:[1,0]
	v_pk_fma_f32 v[170:171], v[36:37], v[14:15], v[170:171]
	v_pk_mul_f32 v[12:13], v[154:155], v[154:155]
	v_pk_fma_f32 v[12:13], v[156:157], v[156:157], v[12:13]
	v_pk_fma_f32 v[12:13], v[158:159], v[158:159], v[12:13]
	v_pk_fma_f32 v[12:13], v[160:161], v[160:161], v[12:13]
	v_pk_fma_f32 v[12:13], v[162:163], v[162:163], v[12:13]
	v_pk_fma_f32 v[12:13], v[164:165], v[164:165], v[12:13]
	v_pk_fma_f32 v[12:13], v[168:169], v[168:169], v[12:13]
	v_pk_fma_f32 v[12:13], v[170:171], v[170:171], v[12:13]
	v_add_f32_e32 v5, v12, v13
	s_nop 1
	v_add_f32_dpp v5, v5, v5 quad_perm:[1,0,3,2] row_mask:0xf bank_mask:0xf
	s_nop 1
	v_add_f32_dpp v5, v5, v5 quad_perm:[2,3,0,1] row_mask:0xf bank_mask:0xf
	s_nop 1
	v_add_f32_dpp v5, v5, v5 row_half_mirror row_mask:0xf bank_mask:0xf
	s_nop 1
	v_add_f32_dpp v5, v5, v5 row_mirror row_mask:0xf bank_mask:0xf
	s_nop 1
	v_add_f32_dpp v5, v5, v5 row_bcast:15 row_mask:0xa bank_mask:0xf
	s_nop 1
	v_add_f32_dpp v5, v5, v5 row_bcast:31 row_mask:0xc bank_mask:0xf
	s_nop 1
	v_readlane_b32 s32, v5, 63
	s_nop 1
	v_mov_b32_e32 v6, s32
	v_fmamk_f32 v6, v6, 0x3a800000, v146
	v_rsq_f32_e32 v6, v6
	s_nop 0
	v_mov_b32_e32 v10, v6
	v_pk_mul_f32 v[14:15], v[154:155], v[10:11] op_sel_hi:[1,0]
	v_pk_fma_f32 v[16:17], v[54:55], v[14:15], v[38:39]
	v_pk_mul_f32 v[14:15], v[156:157], v[10:11] op_sel_hi:[1,0]
	v_pk_fma_f32 v[18:19], v[56:57], v[14:15], v[40:41]
	v_cvt_pk_bf16_f32 v172, v16, v17
	v_cvt_pk_bf16_f32 v173, v18, v19
	v_pk_mul_f32 v[14:15], v[158:159], v[10:11] op_sel_hi:[1,0]
	v_pk_fma_f32 v[16:17], v[58:59], v[14:15], v[42:43]
	v_pk_mul_f32 v[14:15], v[160:161], v[10:11] op_sel_hi:[1,0]
	v_pk_fma_f32 v[18:19], v[60:61], v[14:15], v[44:45]
	v_cvt_pk_bf16_f32 v176, v16, v17
	v_cvt_pk_bf16_f32 v177, v18, v19
	v_pk_mul_f32 v[14:15], v[162:163], v[10:11] op_sel_hi:[1,0]
	v_pk_fma_f32 v[16:17], v[62:63], v[14:15], v[46:47]
	v_pk_mul_f32 v[14:15], v[164:165], v[10:11] op_sel_hi:[1,0]
	v_pk_fma_f32 v[18:19], v[64:65], v[14:15], v[48:49]
	v_cvt_pk_bf16_f32 v204, v16, v17
	v_cvt_pk_bf16_f32 v205, v18, v19
	v_pk_mul_f32 v[14:15], v[168:169], v[10:11] op_sel_hi:[1,0]
	v_pk_fma_f32 v[16:17], v[66:67], v[14:15], v[50:51]
	v_pk_mul_f32 v[14:15], v[170:171], v[10:11] op_sel_hi:[1,0]
	v_pk_fma_f32 v[18:19], v[68:69], v[14:15], v[52:53]
	v_cvt_pk_bf16_f32 v214, v16, v17
	v_cvt_pk_bf16_f32 v215, v18, v19
	global_store_dwordx2 v1, v[172:173], s[62:63] offset:0
	global_store_dwordx2 v1, v[176:177], s[62:63] offset:512
	global_store_dwordx2 v1, v[204:205], s[62:63] offset:1024
	global_store_dwordx2 v1, v[214:215], s[62:63] offset:1536
	global_store_dwordx4 v0, v[154:157], s[46:47] offset:0
	global_store_dwordx4 v0, v[158:161], s[46:47] offset:1024
	global_store_dwordx4 v0, v[162:165], s[46:47] offset:2048
	global_store_dwordx4 v0, v[168:171], s[46:47] offset:3072
	s_add_u32 s46, s46, 0x1000
	s_addc_u32 s47, s47, 0
	s_add_u32 s62, s62, 0x800
	s_addc_u32 s63, s63, 0
	s_waitcnt vmcnt(24)
	v_lshlrev_b32_e32 v14, 16, v234
	v_and_b32_e32 v15, 0xffff0000, v234
	v_lshlrev_b32_e32 v16, 16, v236
	v_and_b32_e32 v17, 0xffff0000, v236
	v_lshlrev_b32_e32 v18, 16, v235
	v_and_b32_e32 v19, 0xffff0000, v235
	v_lshlrev_b32_e32 v20, 16, v237
	v_and_b32_e32 v21, 0xffff0000, v237
	v_pk_add_f32 v[234:235], v[14:15], v[16:17]
	v_pk_add_f32 v[236:237], v[18:19], v[20:21]
	v_lshlrev_b32_e32 v14, 16, v238
	v_and_b32_e32 v15, 0xffff0000, v238
	v_lshlrev_b32_e32 v16, 16, v240
	v_and_b32_e32 v17, 0xffff0000, v240
	v_lshlrev_b32_e32 v18, 16, v239
	v_and_b32_e32 v19, 0xffff0000, v239
	v_lshlrev_b32_e32 v20, 16, v241
	v_and_b32_e32 v21, 0xffff0000, v241
	v_pk_add_f32 v[238:239], v[14:15], v[16:17]
	v_pk_add_f32 v[240:241], v[18:19], v[20:21]
	v_lshlrev_b32_e32 v14, 16, v242
	v_and_b32_e32 v15, 0xffff0000, v242
	v_lshlrev_b32_e32 v16, 16, v244
	v_and_b32_e32 v17, 0xffff0000, v244
	v_lshlrev_b32_e32 v18, 16, v243
	v_and_b32_e32 v19, 0xffff0000, v243
	v_lshlrev_b32_e32 v20, 16, v245
	v_and_b32_e32 v21, 0xffff0000, v245
	v_pk_add_f32 v[242:243], v[14:15], v[16:17]
	v_pk_add_f32 v[244:245], v[18:19], v[20:21]
	v_lshlrev_b32_e32 v14, 16, v246
	v_and_b32_e32 v15, 0xffff0000, v246
	v_lshlrev_b32_e32 v16, 16, v248
	v_and_b32_e32 v17, 0xffff0000, v248
	v_lshlrev_b32_e32 v18, 16, v247
	v_and_b32_e32 v19, 0xffff0000, v247
	v_lshlrev_b32_e32 v20, 16, v249
	v_and_b32_e32 v21, 0xffff0000, v249
	v_pk_add_f32 v[246:247], v[14:15], v[16:17]
	v_pk_add_f32 v[248:249], v[18:19], v[20:21]
	v_pk_mul_f32 v[12:13], v[234:235], v[234:235]
	v_pk_fma_f32 v[12:13], v[236:237], v[236:237], v[12:13]
	v_pk_fma_f32 v[12:13], v[238:239], v[238:239], v[12:13]
	v_pk_fma_f32 v[12:13], v[240:241], v[240:241], v[12:13]
	v_pk_fma_f32 v[12:13], v[242:243], v[242:243], v[12:13]
	v_pk_fma_f32 v[12:13], v[244:245], v[244:245], v[12:13]
	v_pk_fma_f32 v[12:13], v[246:247], v[246:247], v[12:13]
	v_pk_fma_f32 v[12:13], v[248:249], v[248:249], v[12:13]
	v_add_f32_e32 v5, v12, v13
	s_nop 1
	v_add_f32_dpp v5, v5, v5 quad_perm:[1,0,3,2] row_mask:0xf bank_mask:0xf
	s_nop 1
	v_add_f32_dpp v5, v5, v5 quad_perm:[2,3,0,1] row_mask:0xf bank_mask:0xf
	s_nop 1
	v_add_f32_dpp v5, v5, v5 row_half_mirror row_mask:0xf bank_mask:0xf
	s_nop 1
	v_add_f32_dpp v5, v5, v5 row_mirror row_mask:0xf bank_mask:0xf
	s_nop 1
	v_add_f32_dpp v5, v5, v5 row_bcast:15 row_mask:0xa bank_mask:0xf
	s_nop 1
	v_add_f32_dpp v5, v5, v5 row_bcast:31 row_mask:0xc bank_mask:0xf
	s_nop 1
	v_readlane_b32 s32, v5, 63
	s_nop 1
	v_mov_b32_e32 v6, s32
	v_fmamk_f32 v6, v6, 0x3a800000, v146
	v_rsq_f32_e32 v6, v6
	s_nop 0
	v_mul_f32_e32 v8, 0.5, v6
	v_pk_mul_f32 v[14:15], v[234:235], v[8:9] op_sel_hi:[1,0]
	v_pk_fma_f32 v[218:219], v[22:23], v[14:15], v[218:219]
	v_pk_mul_f32 v[14:15], v[236:237], v[8:9] op_sel_hi:[1,0]
	v_pk_fma_f32 v[220:221], v[24:25], v[14:15], v[220:221]
	v_pk_mul_f32 v[14:15], v[238:239], v[8:9] op_sel_hi:[1,0]
	v_pk_fma_f32 v[222:223], v[26:27], v[14:15], v[222:223]
	v_pk_mul_f32 v[14:15], v[240:241], v[8:9] op_sel_hi:[1,0]
	v_pk_fma_f32 v[224:225], v[28:29], v[14:15], v[224:225]
	v_pk_mul_f32 v[14:15], v[242:243], v[8:9] op_sel_hi:[1,0]
	v_pk_fma_f32 v[226:227], v[30:31], v[14:15], v[226:227]
	v_pk_mul_f32 v[14:15], v[244:245], v[8:9] op_sel_hi:[1,0]
	v_pk_fma_f32 v[228:229], v[32:33], v[14:15], v[228:229]
	v_pk_mul_f32 v[14:15], v[246:247], v[8:9] op_sel_hi:[1,0]
	v_pk_fma_f32 v[230:231], v[34:35], v[14:15], v[230:231]
	v_pk_mul_f32 v[14:15], v[248:249], v[8:9] op_sel_hi:[1,0]
	v_pk_fma_f32 v[232:233], v[36:37], v[14:15], v[232:233]
	v_pk_mul_f32 v[12:13], v[218:219], v[218:219]
	v_pk_fma_f32 v[12:13], v[220:221], v[220:221], v[12:13]
	v_pk_fma_f32 v[12:13], v[222:223], v[222:223], v[12:13]
	v_pk_fma_f32 v[12:13], v[224:225], v[224:225], v[12:13]
	v_pk_fma_f32 v[12:13], v[226:227], v[226:227], v[12:13]
	v_pk_fma_f32 v[12:13], v[228:229], v[228:229], v[12:13]
	v_pk_fma_f32 v[12:13], v[230:231], v[230:231], v[12:13]
	v_pk_fma_f32 v[12:13], v[232:233], v[232:233], v[12:13]
	v_add_f32_e32 v5, v12, v13
	s_nop 1
	v_add_f32_dpp v5, v5, v5 quad_perm:[1,0,3,2] row_mask:0xf bank_mask:0xf
	s_nop 1
	v_add_f32_dpp v5, v5, v5 quad_perm:[2,3,0,1] row_mask:0xf bank_mask:0xf
	s_nop 1
	v_add_f32_dpp v5, v5, v5 row_half_mirror row_mask:0xf bank_mask:0xf
	s_nop 1
	v_add_f32_dpp v5, v5, v5 row_mirror row_mask:0xf bank_mask:0xf
	s_nop 1
	v_add_f32_dpp v5, v5, v5 row_bcast:15 row_mask:0xa bank_mask:0xf
	s_nop 1
	v_add_f32_dpp v5, v5, v5 row_bcast:31 row_mask:0xc bank_mask:0xf
	s_nop 1
	v_readlane_b32 s32, v5, 63
	s_nop 1
	v_mov_b32_e32 v6, s32
	v_fmamk_f32 v6, v6, 0x3a800000, v146
	v_rsq_f32_e32 v6, v6
	s_nop 0
	v_mov_b32_e32 v10, v6
	v_pk_mul_f32 v[14:15], v[218:219], v[10:11] op_sel_hi:[1,0]
	v_pk_fma_f32 v[16:17], v[54:55], v[14:15], v[38:39]
	v_pk_mul_f32 v[14:15], v[220:221], v[10:11] op_sel_hi:[1,0]
	v_pk_fma_f32 v[18:19], v[56:57], v[14:15], v[40:41]
	v_cvt_pk_bf16_f32 v234, v16, v17
	v_cvt_pk_bf16_f32 v235, v18, v19
	v_pk_mul_f32 v[14:15], v[222:223], v[10:11] op_sel_hi:[1,0]
	v_pk_fma_f32 v[16:17], v[58:59], v[14:15], v[42:43]
	v_pk_mul_f32 v[14:15], v[224:225], v[10:11] op_sel_hi:[1,0]
	v_pk_fma_f32 v[18:19], v[60:61], v[14:15], v[44:45]
	v_cvt_pk_bf16_f32 v238, v16, v17
	v_cvt_pk_bf16_f32 v239, v18, v19
	v_pk_mul_f32 v[14:15], v[226:227], v[10:11] op_sel_hi:[1,0]
	v_pk_fma_f32 v[16:17], v[62:63], v[14:15], v[46:47]
	v_pk_mul_f32 v[14:15], v[228:229], v[10:11] op_sel_hi:[1,0]
	v_pk_fma_f32 v[18:19], v[64:65], v[14:15], v[48:49]
	v_cvt_pk_bf16_f32 v242, v16, v17
	v_cvt_pk_bf16_f32 v243, v18, v19
	v_pk_mul_f32 v[14:15], v[230:231], v[10:11] op_sel_hi:[1,0]
	v_pk_fma_f32 v[16:17], v[66:67], v[14:15], v[50:51]
	v_pk_mul_f32 v[14:15], v[232:233], v[10:11] op_sel_hi:[1,0]
	v_pk_fma_f32 v[18:19], v[68:69], v[14:15], v[52:53]
	v_cvt_pk_bf16_f32 v246, v16, v17
	v_cvt_pk_bf16_f32 v247, v18, v19
	global_store_dwordx2 v1, v[234:235], s[62:63] offset:0
	global_store_dwordx2 v1, v[238:239], s[62:63] offset:512
	global_store_dwordx2 v1, v[242:243], s[62:63] offset:1024
	global_store_dwordx2 v1, v[246:247], s[62:63] offset:1536
	global_store_dwordx4 v0, v[218:221], s[46:47] offset:0
	global_store_dwordx4 v0, v[222:225], s[46:47] offset:1024
	global_store_dwordx4 v0, v[226:229], s[46:47] offset:2048
	global_store_dwordx4 v0, v[230:233], s[46:47] offset:3072
	s_add_u32 s46, s46, 0x1000
	s_addc_u32 s47, s47, 0
	s_add_u32 s62, s62, 0x800
	s_addc_u32 s63, s63, 0
	s_branch .Lnorm0_done
.Lnorm0_first:
	v_readlane_b32 s2, v255, 0
	v_readfirstlane_b32 s7, v147
	s_load_dwordx2 s[4:5], s[0:1], 0x90
	s_load_dwordx2 s[12:13], s[0:1], 0x98
	s_load_dwordx2 s[14:15], s[0:1], 0x40
	s_load_dwordx2 s[58:59], s[0:1], 0x0
	s_load_dwordx2 s[60:61], s[0:1], 0x8
	v_and_b32_e32 v0, 63, v147
	v_lshlrev_b32_e32 v1, 3, v0
	v_lshlrev_b32_e32 v0, 4, v0
	s_lshr_b32 s7, s7, 6
	s_and_b32 s27, s2, 6
	s_lshl_b32 s27, s27, 5
	s_and_b32 s37, s2, 0x39
	s_or_b32 s27, s27, s37
	s_lshr_b32 s37, s2, 6
	s_lshl_b32 s37, s37, 1
	s_or_b32 s2, s27, s37
	s_lshl_b32 s2, s2, 3
	s_add_u32 s2, s2, s7
	s_lshl_b32 s24, s2, 2
	s_sub_u32 s27, s24, 0x1000
	s_lshr_b32 s27, s27, 10
	s_add_u32 s27, s27, 1
	s_cmp_lt_u32 s24, 0x1000
	s_cselect_b32 s30, 0, s27
	v_mov_b32_e32 v3, v0
	v_add_u32_e32 v4, 0x1000, v0
	s_waitcnt lgkmcnt(0)
	s_lshl_b32 s27, s24, 11
	s_add_u32 s62, s12, s27
	s_addc_u32 s63, s13, 0
	s_add_u32 s62, s62, 0x1000000
	s_addc_u32 s63, s63, 0
	s_lshl_b32 s27, s24, 12
	s_add_u32 s46, s4, s27
	s_addc_u32 s47, s5, 0
	s_sub_u32 s37, s27, 0x1000000
	s_cmp_lt_u32 s24, 0x1000
	s_cselect_b32 s4, s58, s60
	s_cselect_b32 s5, s59, s61
	s_cselect_b32 s27, s27, s37
	s_add_u32 s4, s4, s27
	s_addc_u32 s5, s5, 0
	s_mul_i32 s27, s70, 5
	s_add_u32 s27, s27, s30
	s_mul_i32 s27, s27, 0x9000
	s_add_u32 s27, s27, 0x100000
	s_add_u32 s88, s12, s27
	s_addc_u32 s89, s13, 0
	s_mul_i32 s27, s70, 0x3000
	s_add_u32 s14, s14, s27
	s_addc_u32 s15, s15, 0
	global_load_dwordx4 v[22:25], v3, s[88:89] offset:0
	global_load_dwordx4 v[38:41], v4, s[88:89] offset:0
	global_load_dwordx4 v[54:57], v0, s[14:15] offset:0
	global_load_dwordx4 v[26:29], v3, s[88:89] offset:1024
	global_load_dwordx4 v[42:45], v4, s[88:89] offset:1024
	global_load_dwordx4 v[58:61], v0, s[14:15] offset:1024
	global_load_dwordx4 v[30:33], v3, s[88:89] offset:2048
	global_load_dwordx4 v[46:49], v4, s[88:89] offset:2048
	global_load_dwordx4 v[62:65], v0, s[14:15] offset:2048
	global_load_dwordx4 v[34:37], v3, s[88:89] offset:3072
	global_load_dwordx4 v[50:53], v4, s[88:89] offset:3072
	global_load_dwordx4 v[66:69], v0, s[14:15] offset:3072
	global_load_dwordx4 v[70:73], v0, s[4:5] offset:0 nt
	global_load_dwordx4 v[74:77], v0, s[4:5] offset:1024 nt
	global_load_dwordx4 v[78:81], v0, s[4:5] offset:2048 nt
	global_load_dwordx4 v[82:85], v0, s[4:5] offset:3072 nt
	s_add_u32 s4, s4, 0x1000
	s_addc_u32 s5, s5, 0
	global_load_dwordx4 v[86:89], v0, s[4:5] offset:0 nt
	global_load_dwordx4 v[90:93], v0, s[4:5] offset:1024 nt
	global_load_dwordx4 v[94:97], v0, s[4:5] offset:2048 nt
	global_load_dwordx4 v[98:101], v0, s[4:5] offset:3072 nt
	s_add_u32 s4, s4, 0x1000
	s_addc_u32 s5, s5, 0
	global_load_dwordx4 v[102:105], v0, s[4:5] offset:0 nt
	global_load_dwordx4 v[106:109], v0, s[4:5] offset:1024 nt
	global_load_dwordx4 v[110:113], v0, s[4:5] offset:2048 nt
	global_load_dwordx4 v[114:117], v0, s[4:5] offset:3072 nt
	s_add_u32 s4, s4, 0x1000
	s_addc_u32 s5, s5, 0
	s_waitcnt vmcnt(8)
	v_pk_add_f32 v[38:39], v[38:39], 1.0 op_sel_hi:[1,0]
	v_pk_add_f32 v[40:41], v[40:41], 1.0 op_sel_hi:[1,0]
	v_pk_add_f32 v[42:43], v[42:43], 1.0 op_sel_hi:[1,0]
	v_pk_add_f32 v[44:45], v[44:45], 1.0 op_sel_hi:[1,0]
	v_pk_add_f32 v[46:47], v[46:47], 1.0 op_sel_hi:[1,0]
	v_pk_add_f32 v[48:49], v[48:49], 1.0 op_sel_hi:[1,0]
	v_pk_add_f32 v[50:51], v[50:51], 1.0 op_sel_hi:[1,0]
	v_pk_add_f32 v[52:53], v[52:53], 1.0 op_sel_hi:[1,0]
	v_pk_mul_f32 v[12:13], v[70:71], v[70:71]
	v_pk_fma_f32 v[12:13], v[72:73], v[72:73], v[12:13]
	v_pk_fma_f32 v[12:13], v[74:75], v[74:75], v[12:13]
	v_pk_fma_f32 v[12:13], v[76:77], v[76:77], v[12:13]
	v_pk_fma_f32 v[12:13], v[78:79], v[78:79], v[12:13]
	v_pk_fma_f32 v[12:13], v[80:81], v[80:81], v[12:13]
	v_pk_fma_f32 v[12:13], v[82:83], v[82:83], v[12:13]
	v_pk_fma_f32 v[12:13], v[84:85], v[84:85], v[12:13]
	v_add_f32_e32 v5, v12, v13
	s_nop 1
	v_add_f32_dpp v5, v5, v5 quad_perm:[1,0,3,2] row_mask:0xf bank_mask:0xf
	s_nop 1
	v_add_f32_dpp v5, v5, v5 quad_perm:[2,3,0,1] row_mask:0xf bank_mask:0xf
	s_nop 1
	v_add_f32_dpp v5, v5, v5 row_half_mirror row_mask:0xf bank_mask:0xf
	s_nop 1
	v_add_f32_dpp v5, v5, v5 row_mirror row_mask:0xf bank_mask:0xf
	s_nop 1
	v_add_f32_dpp v5, v5, v5 row_bcast:15 row_mask:0xa bank_mask:0xf
	s_nop 1
	v_add_f32_dpp v5, v5, v5 row_bcast:31 row_mask:0xc bank_mask:0xf
	s_nop 1
	v_readlane_b32 s32, v5, 63
	s_nop 1
	v_mov_b32_e32 v6, s32
	v_fmamk_f32 v6, v6, 0x3a800000, v146
	v_rsq_f32_e32 v6, v6
	s_nop 0
	v_mov_b32_e32 v10, v6
	v_pk_mul_f32 v[14:15], v[70:71], v[10:11] op_sel_hi:[1,0]
	v_pk_mul_f32 v[14:15], v[54:55], v[14:15]
	v_pk_fma_f32 v[16:17], v[38:39], v[14:15], v[22:23]
	v_pk_mul_f32 v[14:15], v[72:73], v[10:11] op_sel_hi:[1,0]
	v_pk_mul_f32 v[14:15], v[56:57], v[14:15]
	v_pk_fma_f32 v[18:19], v[40:41], v[14:15], v[24:25]
	v_cvt_pk_bf16_f32 v118, v16, v17
	v_cvt_pk_bf16_f32 v119, v18, v19
	v_pk_mul_f32 v[14:15], v[74:75], v[10:11] op_sel_hi:[1,0]
	v_pk_mul_f32 v[14:15], v[58:59], v[14:15]
	v_pk_fma_f32 v[16:17], v[42:43], v[14:15], v[26:27]
	v_pk_mul_f32 v[14:15], v[76:77], v[10:11] op_sel_hi:[1,0]
	v_pk_mul_f32 v[14:15], v[60:61], v[14:15]
	v_pk_fma_f32 v[18:19], v[44:45], v[14:15], v[28:29]
	v_cvt_pk_bf16_f32 v120, v16, v17
	v_cvt_pk_bf16_f32 v121, v18, v19
	v_pk_mul_f32 v[14:15], v[78:79], v[10:11] op_sel_hi:[1,0]
	v_pk_mul_f32 v[14:15], v[62:63], v[14:15]
	v_pk_fma_f32 v[16:17], v[46:47], v[14:15], v[30:31]
	v_pk_mul_f32 v[14:15], v[80:81], v[10:11] op_sel_hi:[1,0]
	v_pk_mul_f32 v[14:15], v[64:65], v[14:15]
	v_pk_fma_f32 v[18:19], v[48:49], v[14:15], v[32:33]
	v_cvt_pk_bf16_f32 v122, v16, v17
	v_cvt_pk_bf16_f32 v123, v18, v19
	v_pk_mul_f32 v[14:15], v[82:83], v[10:11] op_sel_hi:[1,0]
	v_pk_mul_f32 v[14:15], v[66:67], v[14:15]
	v_pk_fma_f32 v[16:17], v[50:51], v[14:15], v[34:35]
	v_pk_mul_f32 v[14:15], v[84:85], v[10:11] op_sel_hi:[1,0]
	v_pk_mul_f32 v[14:15], v[68:69], v[14:15]
	v_pk_fma_f32 v[18:19], v[52:53], v[14:15], v[36:37]
	v_cvt_pk_bf16_f32 v124, v16, v17
	v_cvt_pk_bf16_f32 v125, v18, v19
	global_store_dwordx2 v1, v[118:119], s[62:63] offset:0
	global_store_dwordx2 v1, v[120:121], s[62:63] offset:512
	global_store_dwordx2 v1, v[122:123], s[62:63] offset:1024
	global_store_dwordx2 v1, v[124:125], s[62:63] offset:1536
	global_store_dwordx4 v0, v[70:73], s[46:47] offset:0
	global_store_dwordx4 v0, v[74:77], s[46:47] offset:1024
	global_store_dwordx4 v0, v[78:81], s[46:47] offset:2048
	global_store_dwordx4 v0, v[82:85], s[46:47] offset:3072
	s_add_u32 s46, s46, 0x1000
	s_addc_u32 s47, s47, 0
	s_add_u32 s62, s62, 0x800
	s_addc_u32 s63, s63, 0
	s_nop 1
	global_load_dwordx4 v[70:73], v0, s[4:5] offset:0 nt
	global_load_dwordx4 v[74:77], v0, s[4:5] offset:1024 nt
	global_load_dwordx4 v[78:81], v0, s[4:5] offset:2048 nt
	global_load_dwordx4 v[82:85], v0, s[4:5] offset:3072 nt
	s_add_u32 s4, s4, 0x1000
	s_addc_u32 s5, s5, 0
	s_waitcnt vmcnt(16)
	v_pk_mul_f32 v[12:13], v[86:87], v[86:87]
	v_pk_fma_f32 v[12:13], v[88:89], v[88:89], v[12:13]
	v_pk_fma_f32 v[12:13], v[90:91], v[90:91], v[12:13]
	v_pk_fma_f32 v[12:13], v[92:93], v[92:93], v[12:13]
	v_pk_fma_f32 v[12:13], v[94:95], v[94:95], v[12:13]
	v_pk_fma_f32 v[12:13], v[96:97], v[96:97], v[12:13]
	v_pk_fma_f32 v[12:13], v[98:99], v[98:99], v[12:13]
	v_pk_fma_f32 v[12:13], v[100:101], v[100:101], v[12:13]
	v_add_f32_e32 v5, v12, v13
	s_nop 1
	v_add_f32_dpp v5, v5, v5 quad_perm:[1,0,3,2] row_mask:0xf bank_mask:0xf
	s_nop 1
	v_add_f32_dpp v5, v5, v5 quad_perm:[2,3,0,1] row_mask:0xf bank_mask:0xf
	s_nop 1
	v_add_f32_dpp v5, v5, v5 row_half_mirror row_mask:0xf bank_mask:0xf
	s_nop 1
	v_add_f32_dpp v5, v5, v5 row_mirror row_mask:0xf bank_mask:0xf
	s_nop 1
	v_add_f32_dpp v5, v5, v5 row_bcast:15 row_mask:0xa bank_mask:0xf
	s_nop 1
	v_add_f32_dpp v5, v5, v5 row_bcast:31 row_mask:0xc bank_mask:0xf
	s_nop 1
	v_readlane_b32 s32, v5, 63
	s_nop 1
	v_mov_b32_e32 v6, s32
	v_fmamk_f32 v6, v6, 0x3a800000, v146
	v_rsq_f32_e32 v6, v6
	s_nop 0
	v_mov_b32_e32 v10, v6
	v_pk_mul_f32 v[14:15], v[86:87], v[10:11] op_sel_hi:[1,0]
	v_pk_mul_f32 v[14:15], v[54:55], v[14:15]
	v_pk_fma_f32 v[16:17], v[38:39], v[14:15], v[22:23]
	v_pk_mul_f32 v[14:15], v[88:89], v[10:11] op_sel_hi:[1,0]
	v_pk_mul_f32 v[14:15], v[56:57], v[14:15]
	v_pk_fma_f32 v[18:19], v[40:41], v[14:15], v[24:25]
	v_cvt_pk_bf16_f32 v118, v16, v17
	v_cvt_pk_bf16_f32 v119, v18, v19
	v_pk_mul_f32 v[14:15], v[90:91], v[10:11] op_sel_hi:[1,0]
	v_pk_mul_f32 v[14:15], v[58:59], v[14:15]
	v_pk_fma_f32 v[16:17], v[42:43], v[14:15], v[26:27]
	v_pk_mul_f32 v[14:15], v[92:93], v[10:11] op_sel_hi:[1,0]
	v_pk_mul_f32 v[14:15], v[60:61], v[14:15]
	v_pk_fma_f32 v[18:19], v[44:45], v[14:15], v[28:29]
	v_cvt_pk_bf16_f32 v120, v16, v17
	v_cvt_pk_bf16_f32 v121, v18, v19
	v_pk_mul_f32 v[14:15], v[94:95], v[10:11] op_sel_hi:[1,0]
	v_pk_mul_f32 v[14:15], v[62:63], v[14:15]
	v_pk_fma_f32 v[16:17], v[46:47], v[14:15], v[30:31]
	v_pk_mul_f32 v[14:15], v[96:97], v[10:11] op_sel_hi:[1,0]
	v_pk_mul_f32 v[14:15], v[64:65], v[14:15]
	v_pk_fma_f32 v[18:19], v[48:49], v[14:15], v[32:33]
	v_cvt_pk_bf16_f32 v122, v16, v17
	v_cvt_pk_bf16_f32 v123, v18, v19
	v_pk_mul_f32 v[14:15], v[98:99], v[10:11] op_sel_hi:[1,0]
	v_pk_mul_f32 v[14:15], v[66:67], v[14:15]
	v_pk_fma_f32 v[16:17], v[50:51], v[14:15], v[34:35]
	v_pk_mul_f32 v[14:15], v[100:101], v[10:11] op_sel_hi:[1,0]
	v_pk_mul_f32 v[14:15], v[68:69], v[14:15]
	v_pk_fma_f32 v[18:19], v[52:53], v[14:15], v[36:37]
	v_cvt_pk_bf16_f32 v124, v16, v17
	v_cvt_pk_bf16_f32 v125, v18, v19
	global_store_dwordx2 v1, v[118:119], s[62:63] offset:0
	global_store_dwordx2 v1, v[120:121], s[62:63] offset:512
	global_store_dwordx2 v1, v[122:123], s[62:63] offset:1024
	global_store_dwordx2 v1, v[124:125], s[62:63] offset:1536
	global_store_dwordx4 v0, v[86:89], s[46:47] offset:0
	global_store_dwordx4 v0, v[90:93], s[46:47] offset:1024
	global_store_dwordx4 v0, v[94:97], s[46:47] offset:2048
	global_store_dwordx4 v0, v[98:101], s[46:47] offset:3072
	s_add_u32 s46, s46, 0x1000
	s_addc_u32 s47, s47, 0
	s_add_u32 s62, s62, 0x800
	s_addc_u32 s63, s63, 0
	s_waitcnt vmcnt(20)
	v_pk_mul_f32 v[12:13], v[102:103], v[102:103]
	v_pk_fma_f32 v[12:13], v[104:105], v[104:105], v[12:13]
	v_pk_fma_f32 v[12:13], v[106:107], v[106:107], v[12:13]
	v_pk_fma_f32 v[12:13], v[108:109], v[108:109], v[12:13]
	v_pk_fma_f32 v[12:13], v[110:111], v[110:111], v[12:13]
	v_pk_fma_f32 v[12:13], v[112:113], v[112:113], v[12:13]
	v_pk_fma_f32 v[12:13], v[114:115], v[114:115], v[12:13]
	v_pk_fma_f32 v[12:13], v[116:117], v[116:117], v[12:13]
	v_add_f32_e32 v5, v12, v13
	s_nop 1
	v_add_f32_dpp v5, v5, v5 quad_perm:[1,0,3,2] row_mask:0xf bank_mask:0xf
	s_nop 1
	v_add_f32_dpp v5, v5, v5 quad_perm:[2,3,0,1] row_mask:0xf bank_mask:0xf
	s_nop 1
	v_add_f32_dpp v5, v5, v5 row_half_mirror row_mask:0xf bank_mask:0xf
	s_nop 1
	v_add_f32_dpp v5, v5, v5 row_mirror row_mask:0xf bank_mask:0xf
	s_nop 1
	v_add_f32_dpp v5, v5, v5 row_bcast:15 row_mask:0xa bank_mask:0xf
	s_nop 1
	v_add_f32_dpp v5, v5, v5 row_bcast:31 row_mask:0xc bank_mask:0xf
	s_nop 1
	v_readlane_b32 s32, v5, 63
	s_nop 1
	v_mov_b32_e32 v6, s32
	v_fmamk_f32 v6, v6, 0x3a800000, v146
	v_rsq_f32_e32 v6, v6
	s_nop 0
	v_mov_b32_e32 v10, v6
	v_pk_mul_f32 v[14:15], v[102:103], v[10:11] op_sel_hi:[1,0]
	v_pk_mul_f32 v[14:15], v[54:55], v[14:15]
	v_pk_fma_f32 v[16:17], v[38:39], v[14:15], v[22:23]
	v_pk_mul_f32 v[14:15], v[104:105], v[10:11] op_sel_hi:[1,0]
	v_pk_mul_f32 v[14:15], v[56:57], v[14:15]
	v_pk_fma_f32 v[18:19], v[40:41], v[14:15], v[24:25]
	v_cvt_pk_bf16_f32 v118, v16, v17
	v_cvt_pk_bf16_f32 v119, v18, v19
	v_pk_mul_f32 v[14:15], v[106:107], v[10:11] op_sel_hi:[1,0]
	v_pk_mul_f32 v[14:15], v[58:59], v[14:15]
	v_pk_fma_f32 v[16:17], v[42:43], v[14:15], v[26:27]
	v_pk_mul_f32 v[14:15], v[108:109], v[10:11] op_sel_hi:[1,0]
	v_pk_mul_f32 v[14:15], v[60:61], v[14:15]
	v_pk_fma_f32 v[18:19], v[44:45], v[14:15], v[28:29]
	v_cvt_pk_bf16_f32 v120, v16, v17
	v_cvt_pk_bf16_f32 v121, v18, v19
	v_pk_mul_f32 v[14:15], v[110:111], v[10:11] op_sel_hi:[1,0]
	v_pk_mul_f32 v[14:15], v[62:63], v[14:15]
	v_pk_fma_f32 v[16:17], v[46:47], v[14:15], v[30:31]
	v_pk_mul_f32 v[14:15], v[112:113], v[10:11] op_sel_hi:[1,0]
	v_pk_mul_f32 v[14:15], v[64:65], v[14:15]
	v_pk_fma_f32 v[18:19], v[48:49], v[14:15], v[32:33]
	v_cvt_pk_bf16_f32 v122, v16, v17
	v_cvt_pk_bf16_f32 v123, v18, v19
	v_pk_mul_f32 v[14:15], v[114:115], v[10:11] op_sel_hi:[1,0]
	v_pk_mul_f32 v[14:15], v[66:67], v[14:15]
	v_pk_fma_f32 v[16:17], v[50:51], v[14:15], v[34:35]
	v_pk_mul_f32 v[14:15], v[116:117], v[10:11] op_sel_hi:[1,0]
	v_pk_mul_f32 v[14:15], v[68:69], v[14:15]
	v_pk_fma_f32 v[18:19], v[52:53], v[14:15], v[36:37]
	v_cvt_pk_bf16_f32 v124, v16, v17
	v_cvt_pk_bf16_f32 v125, v18, v19
	global_store_dwordx2 v1, v[118:119], s[62:63] offset:0
	global_store_dwordx2 v1, v[120:121], s[62:63] offset:512
	global_store_dwordx2 v1, v[122:123], s[62:63] offset:1024
	global_store_dwordx2 v1, v[124:125], s[62:63] offset:1536
	global_store_dwordx4 v0, v[102:105], s[46:47] offset:0
	global_store_dwordx4 v0, v[106:109], s[46:47] offset:1024
	global_store_dwordx4 v0, v[110:113], s[46:47] offset:2048
	global_store_dwordx4 v0, v[114:117], s[46:47] offset:3072
	s_add_u32 s46, s46, 0x1000
	s_addc_u32 s47, s47, 0
	s_add_u32 s62, s62, 0x800
	s_addc_u32 s63, s63, 0
	s_waitcnt vmcnt(16)
	v_pk_mul_f32 v[12:13], v[70:71], v[70:71]
	v_pk_fma_f32 v[12:13], v[72:73], v[72:73], v[12:13]
	v_pk_fma_f32 v[12:13], v[74:75], v[74:75], v[12:13]
	v_pk_fma_f32 v[12:13], v[76:77], v[76:77], v[12:13]
	v_pk_fma_f32 v[12:13], v[78:79], v[78:79], v[12:13]
	v_pk_fma_f32 v[12:13], v[80:81], v[80:81], v[12:13]
	v_pk_fma_f32 v[12:13], v[82:83], v[82:83], v[12:13]
	v_pk_fma_f32 v[12:13], v[84:85], v[84:85], v[12:13]
	v_add_f32_e32 v5, v12, v13
	s_nop 1
	v_add_f32_dpp v5, v5, v5 quad_perm:[1,0,3,2] row_mask:0xf bank_mask:0xf
	s_nop 1
	v_add_f32_dpp v5, v5, v5 quad_perm:[2,3,0,1] row_mask:0xf bank_mask:0xf
	s_nop 1
	v_add_f32_dpp v5, v5, v5 row_half_mirror row_mask:0xf bank_mask:0xf
	s_nop 1
	v_add_f32_dpp v5, v5, v5 row_mirror row_mask:0xf bank_mask:0xf
	s_nop 1
	v_add_f32_dpp v5, v5, v5 row_bcast:15 row_mask:0xa bank_mask:0xf
	s_nop 1
	v_add_f32_dpp v5, v5, v5 row_bcast:31 row_mask:0xc bank_mask:0xf
	s_nop 1
	v_readlane_b32 s32, v5, 63
	s_nop 1
	v_mov_b32_e32 v6, s32
	v_fmamk_f32 v6, v6, 0x3a800000, v146
	v_rsq_f32_e32 v6, v6
	s_nop 0
	v_mov_b32_e32 v10, v6
	v_pk_mul_f32 v[14:15], v[70:71], v[10:11] op_sel_hi:[1,0]
	v_pk_mul_f32 v[14:15], v[54:55], v[14:15]
	v_pk_fma_f32 v[16:17], v[38:39], v[14:15], v[22:23]
	v_pk_mul_f32 v[14:15], v[72:73], v[10:11] op_sel_hi:[1,0]
	v_pk_mul_f32 v[14:15], v[56:57], v[14:15]
	v_pk_fma_f32 v[18:19], v[40:41], v[14:15], v[24:25]
	v_cvt_pk_bf16_f32 v118, v16, v17
	v_cvt_pk_bf16_f32 v119, v18, v19
	v_pk_mul_f32 v[14:15], v[74:75], v[10:11] op_sel_hi:[1,0]
	v_pk_mul_f32 v[14:15], v[58:59], v[14:15]
	v_pk_fma_f32 v[16:17], v[42:43], v[14:15], v[26:27]
	v_pk_mul_f32 v[14:15], v[76:77], v[10:11] op_sel_hi:[1,0]
	v_pk_mul_f32 v[14:15], v[60:61], v[14:15]
	v_pk_fma_f32 v[18:19], v[44:45], v[14:15], v[28:29]
	v_cvt_pk_bf16_f32 v120, v16, v17
	v_cvt_pk_bf16_f32 v121, v18, v19
	v_pk_mul_f32 v[14:15], v[78:79], v[10:11] op_sel_hi:[1,0]
	v_pk_mul_f32 v[14:15], v[62:63], v[14:15]
	v_pk_fma_f32 v[16:17], v[46:47], v[14:15], v[30:31]
	v_pk_mul_f32 v[14:15], v[80:81], v[10:11] op_sel_hi:[1,0]
	v_pk_mul_f32 v[14:15], v[64:65], v[14:15]
	v_pk_fma_f32 v[18:19], v[48:49], v[14:15], v[32:33]
	v_cvt_pk_bf16_f32 v122, v16, v17
	v_cvt_pk_bf16_f32 v123, v18, v19
	v_pk_mul_f32 v[14:15], v[82:83], v[10:11] op_sel_hi:[1,0]
	v_pk_mul_f32 v[14:15], v[66:67], v[14:15]
	v_pk_fma_f32 v[16:17], v[50:51], v[14:15], v[34:35]
	v_pk_mul_f32 v[14:15], v[84:85], v[10:11] op_sel_hi:[1,0]
	v_pk_mul_f32 v[14:15], v[68:69], v[14:15]
	v_pk_fma_f32 v[18:19], v[52:53], v[14:15], v[36:37]
	v_cvt_pk_bf16_f32 v124, v16, v17
	v_cvt_pk_bf16_f32 v125, v18, v19
	global_store_dwordx2 v1, v[118:119], s[62:63] offset:0
	global_store_dwordx2 v1, v[120:121], s[62:63] offset:512
	global_store_dwordx2 v1, v[122:123], s[62:63] offset:1024
	global_store_dwordx2 v1, v[124:125], s[62:63] offset:1536
	global_store_dwordx4 v0, v[70:73], s[46:47] offset:0
	global_store_dwordx4 v0, v[74:77], s[46:47] offset:1024
	global_store_dwordx4 v0, v[78:81], s[46:47] offset:2048
	global_store_dwordx4 v0, v[82:85], s[46:47] offset:3072
	s_add_u32 s46, s46, 0x1000
	s_addc_u32 s47, s47, 0
	s_add_u32 s62, s62, 0x800
	s_addc_u32 s63, s63, 0

.Lnw_skip_n2:
	s_or_b64 exec, exec, s[40:41]
	s_waitcnt vmcnt(36)
	s_barrier
	global_load_dwordx2 v[86:87], v1, s[58:59] offset:0
	global_load_dwordx2 v[90:91], v1, s[58:59] offset:512
	global_load_dwordx2 v[94:95], v1, s[58:59] offset:1024
	global_load_dwordx2 v[98:99], v1, s[58:59] offset:1536
	global_load_dwordx2 v[88:89], v1, s[60:61] offset:0
	global_load_dwordx2 v[92:93], v1, s[60:61] offset:512
	global_load_dwordx2 v[96:97], v1, s[60:61] offset:1024
	global_load_dwordx2 v[100:101], v1, s[60:61] offset:1536
	s_add_u32 s58, s58, 0x800
	s_addc_u32 s59, s59, 0
	s_add_u32 s60, s60, 0x800
	s_addc_u32 s61, s61, 0
	global_load_dwordx2 v[118:119], v1, s[58:59] offset:0
	global_load_dwordx2 v[122:123], v1, s[58:59] offset:512
	global_load_dwordx2 v[134:135], v1, s[58:59] offset:1024
	global_load_dwordx2 v[138:139], v1, s[58:59] offset:1536
	global_load_dwordx2 v[120:121], v1, s[60:61] offset:0
	global_load_dwordx2 v[124:125], v1, s[60:61] offset:512
	global_load_dwordx2 v[136:137], v1, s[60:61] offset:1024
	global_load_dwordx2 v[140:141], v1, s[60:61] offset:1536
	s_add_u32 s58, s58, 0x800
	s_addc_u32 s59, s59, 0
	s_add_u32 s60, s60, 0x800
	s_addc_u32 s61, s61, 0
	global_load_dwordx2 v[172:173], v1, s[58:59] offset:0
	global_load_dwordx2 v[176:177], v1, s[58:59] offset:512
	global_load_dwordx2 v[204:205], v1, s[58:59] offset:1024
	global_load_dwordx2 v[214:215], v1, s[58:59] offset:1536
	global_load_dwordx2 v[174:175], v1, s[60:61] offset:0
	global_load_dwordx2 v[178:179], v1, s[60:61] offset:512
	global_load_dwordx2 v[206:207], v1, s[60:61] offset:1024
	global_load_dwordx2 v[216:217], v1, s[60:61] offset:1536
	s_add_u32 s58, s58, 0x800
	s_addc_u32 s59, s59, 0
	s_add_u32 s60, s60, 0x800
	s_addc_u32 s61, s61, 0
	global_load_dwordx2 v[234:235], v1, s[58:59] offset:0
	global_load_dwordx2 v[238:239], v1, s[58:59] offset:512
	global_load_dwordx2 v[242:243], v1, s[58:59] offset:1024
	global_load_dwordx2 v[246:247], v1, s[58:59] offset:1536
	global_load_dwordx2 v[236:237], v1, s[60:61] offset:0
	global_load_dwordx2 v[240:241], v1, s[60:61] offset:512
	global_load_dwordx2 v[244:245], v1, s[60:61] offset:1024
	global_load_dwordx2 v[248:249], v1, s[60:61] offset:1536
	s_add_u32 s58, s58, 0x800
	s_addc_u32 s59, s59, 0
	s_add_u32 s60, s60, 0x800
	s_addc_u32 s61, s61, 0
	s_waitcnt vmcnt(24)
	v_lshlrev_b32_e32 v14, 16, v86
	v_and_b32_e32 v15, 0xffff0000, v86
	v_lshlrev_b32_e32 v16, 16, v88
	v_and_b32_e32 v17, 0xffff0000, v88
	v_lshlrev_b32_e32 v18, 16, v87
	v_and_b32_e32 v19, 0xffff0000, v87
	v_lshlrev_b32_e32 v20, 16, v89
	v_and_b32_e32 v21, 0xffff0000, v89
	v_pk_add_f32 v[86:87], v[14:15], v[16:17]
	v_pk_add_f32 v[88:89], v[18:19], v[20:21]
	v_lshlrev_b32_e32 v14, 16, v90
	v_and_b32_e32 v15, 0xffff0000, v90
	v_lshlrev_b32_e32 v16, 16, v92
	v_and_b32_e32 v17, 0xffff0000, v92
	v_lshlrev_b32_e32 v18, 16, v91
	v_and_b32_e32 v19, 0xffff0000, v91
	v_lshlrev_b32_e32 v20, 16, v93
	v_and_b32_e32 v21, 0xffff0000, v93
	v_pk_add_f32 v[90:91], v[14:15], v[16:17]
	v_pk_add_f32 v[92:93], v[18:19], v[20:21]
	v_lshlrev_b32_e32 v14, 16, v94
	v_and_b32_e32 v15, 0xffff0000, v94
	v_lshlrev_b32_e32 v16, 16, v96
	v_and_b32_e32 v17, 0xffff0000, v96
	v_lshlrev_b32_e32 v18, 16, v95
	v_and_b32_e32 v19, 0xffff0000, v95
	v_lshlrev_b32_e32 v20, 16, v97
	v_and_b32_e32 v21, 0xffff0000, v97
	v_pk_add_f32 v[94:95], v[14:15], v[16:17]
	v_pk_add_f32 v[96:97], v[18:19], v[20:21]
	v_lshlrev_b32_e32 v14, 16, v98
	v_and_b32_e32 v15, 0xffff0000, v98
	v_lshlrev_b32_e32 v16, 16, v100
	v_and_b32_e32 v17, 0xffff0000, v100
	v_lshlrev_b32_e32 v18, 16, v99
	v_and_b32_e32 v19, 0xffff0000, v99
	v_lshlrev_b32_e32 v20, 16, v101
	v_and_b32_e32 v21, 0xffff0000, v101
	v_pk_add_f32 v[98:99], v[14:15], v[16:17]
	v_pk_add_f32 v[100:101], v[18:19], v[20:21]
	v_pk_mul_f32 v[12:13], v[86:87], v[86:87]
	v_pk_fma_f32 v[12:13], v[88:89], v[88:89], v[12:13]
	v_pk_fma_f32 v[12:13], v[90:91], v[90:91], v[12:13]
	v_pk_fma_f32 v[12:13], v[92:93], v[92:93], v[12:13]
	v_pk_fma_f32 v[12:13], v[94:95], v[94:95], v[12:13]
	v_pk_fma_f32 v[12:13], v[96:97], v[96:97], v[12:13]
	v_pk_fma_f32 v[12:13], v[98:99], v[98:99], v[12:13]
	v_pk_fma_f32 v[12:13], v[100:101], v[100:101], v[12:13]
	v_add_f32_e32 v5, v12, v13
	s_nop 1
	v_add_f32_dpp v5, v5, v5 quad_perm:[1,0,3,2] row_mask:0xf bank_mask:0xf
	s_nop 1
	v_add_f32_dpp v5, v5, v5 quad_perm:[2,3,0,1] row_mask:0xf bank_mask:0xf
	s_nop 1
	v_add_f32_dpp v5, v5, v5 row_half_mirror row_mask:0xf bank_mask:0xf
	s_nop 1
	v_add_f32_dpp v5, v5, v5 row_mirror row_mask:0xf bank_mask:0xf
	s_nop 1
	v_add_f32_dpp v5, v5, v5 row_bcast:15 row_mask:0xa bank_mask:0xf
	s_nop 1
	v_add_f32_dpp v5, v5, v5 row_bcast:31 row_mask:0xc bank_mask:0xf
	s_nop 1
	v_readlane_b32 s32, v5, 63
	s_nop 1
	v_mov_b32_e32 v6, s32
	v_fmamk_f32 v6, v6, 0x3a800000, v146
	v_rsq_f32_e32 v6, v6
	s_nop 0
	v_mov_b32_e32 v8, v6
	v_pk_mul_f32 v[14:15], v[86:87], v[8:9] op_sel_hi:[1,0]
	v_pk_fma_f32 v[70:71], v[22:23], v[14:15], v[70:71]
	v_pk_mul_f32 v[14:15], v[88:89], v[8:9] op_sel_hi:[1,0]
	v_pk_fma_f32 v[72:73], v[24:25], v[14:15], v[72:73]
	v_pk_mul_f32 v[14:15], v[90:91], v[8:9] op_sel_hi:[1,0]
	v_pk_fma_f32 v[74:75], v[26:27], v[14:15], v[74:75]
	v_pk_mul_f32 v[14:15], v[92:93], v[8:9] op_sel_hi:[1,0]
	v_pk_fma_f32 v[76:77], v[28:29], v[14:15], v[76:77]
	v_pk_mul_f32 v[14:15], v[94:95], v[8:9] op_sel_hi:[1,0]
	v_pk_fma_f32 v[78:79], v[30:31], v[14:15], v[78:79]
	v_pk_mul_f32 v[14:15], v[96:97], v[8:9] op_sel_hi:[1,0]
	v_pk_fma_f32 v[80:81], v[32:33], v[14:15], v[80:81]
	v_pk_mul_f32 v[14:15], v[98:99], v[8:9] op_sel_hi:[1,0]
	v_pk_fma_f32 v[82:83], v[34:35], v[14:15], v[82:83]
	v_pk_mul_f32 v[14:15], v[100:101], v[8:9] op_sel_hi:[1,0]
	v_pk_fma_f32 v[84:85], v[36:37], v[14:15], v[84:85]
	v_pk_mul_f32 v[12:13], v[70:71], v[70:71]
	v_pk_fma_f32 v[12:13], v[72:73], v[72:73], v[12:13]
	v_pk_fma_f32 v[12:13], v[74:75], v[74:75], v[12:13]
	v_pk_fma_f32 v[12:13], v[76:77], v[76:77], v[12:13]
	v_pk_fma_f32 v[12:13], v[78:79], v[78:79], v[12:13]
	v_pk_fma_f32 v[12:13], v[80:81], v[80:81], v[12:13]
	v_pk_fma_f32 v[12:13], v[82:83], v[82:83], v[12:13]
	v_pk_fma_f32 v[12:13], v[84:85], v[84:85], v[12:13]
	v_add_f32_e32 v5, v12, v13
	s_nop 1
	v_add_f32_dpp v5, v5, v5 quad_perm:[1,0,3,2] row_mask:0xf bank_mask:0xf
	s_nop 1
	v_add_f32_dpp v5, v5, v5 quad_perm:[2,3,0,1] row_mask:0xf bank_mask:0xf
	s_nop 1
	v_add_f32_dpp v5, v5, v5 row_half_mirror row_mask:0xf bank_mask:0xf
	s_nop 1
	v_add_f32_dpp v5, v5, v5 row_mirror row_mask:0xf bank_mask:0xf
	s_nop 1
	v_add_f32_dpp v5, v5, v5 row_bcast:15 row_mask:0xa bank_mask:0xf
	s_nop 1
	v_add_f32_dpp v5, v5, v5 row_bcast:31 row_mask:0xc bank_mask:0xf
	s_nop 1
	v_readlane_b32 s32, v5, 63
	s_nop 1
	v_mov_b32_e32 v6, s32
	v_fmamk_f32 v6, v6, 0x3a800000, v146
	v_rsq_f32_e32 v6, v6
	s_nop 0
	v_mov_b32_e32 v10, v6
	v_pk_mul_f32 v[14:15], v[70:71], v[10:11] op_sel_hi:[1,0]
	v_pk_fma_f32 v[16:17], v[54:55], v[14:15], v[38:39]
	v_pk_mul_f32 v[14:15], v[72:73], v[10:11] op_sel_hi:[1,0]
	v_pk_fma_f32 v[18:19], v[56:57], v[14:15], v[40:41]
	v_cvt_pk_bf16_f32 v86, v16, v17
	v_cvt_pk_bf16_f32 v87, v18, v19
	v_pk_mul_f32 v[14:15], v[74:75], v[10:11] op_sel_hi:[1,0]
	v_pk_fma_f32 v[16:17], v[58:59], v[14:15], v[42:43]
	v_pk_mul_f32 v[14:15], v[76:77], v[10:11] op_sel_hi:[1,0]
	v_pk_fma_f32 v[18:19], v[60:61], v[14:15], v[44:45]
	v_cvt_pk_bf16_f32 v90, v16, v17
	v_cvt_pk_bf16_f32 v91, v18, v19
	v_pk_mul_f32 v[14:15], v[78:79], v[10:11] op_sel_hi:[1,0]
	v_pk_fma_f32 v[16:17], v[62:63], v[14:15], v[46:47]
	v_pk_mul_f32 v[14:15], v[80:81], v[10:11] op_sel_hi:[1,0]
	v_pk_fma_f32 v[18:19], v[64:65], v[14:15], v[48:49]
	v_cvt_pk_bf16_f32 v94, v16, v17
	v_cvt_pk_bf16_f32 v95, v18, v19
	v_pk_mul_f32 v[14:15], v[82:83], v[10:11] op_sel_hi:[1,0]
	v_pk_fma_f32 v[16:17], v[66:67], v[14:15], v[50:51]
	v_pk_mul_f32 v[14:15], v[84:85], v[10:11] op_sel_hi:[1,0]
	v_pk_fma_f32 v[18:19], v[68:69], v[14:15], v[52:53]
	v_cvt_pk_bf16_f32 v98, v16, v17
	v_cvt_pk_bf16_f32 v99, v18, v19
	global_store_dwordx2 v1, v[86:87], s[62:63] offset:0
	global_store_dwordx2 v1, v[90:91], s[62:63] offset:512
	global_store_dwordx2 v1, v[94:95], s[62:63] offset:1024
	global_store_dwordx2 v1, v[98:99], s[62:63] offset:1536
	global_store_dwordx4 v0, v[70:73], s[46:47] offset:0
	global_store_dwordx4 v0, v[74:77], s[46:47] offset:1024
	global_store_dwordx4 v0, v[78:81], s[46:47] offset:2048
	global_store_dwordx4 v0, v[82:85], s[46:47] offset:3072
	s_add_u32 s46, s46, 0x1000
	s_addc_u32 s47, s47, 0
	s_add_u32 s62, s62, 0x800
	s_addc_u32 s63, s63, 0
	s_waitcnt vmcnt(24)
	v_lshlrev_b32_e32 v14, 16, v118
	v_and_b32_e32 v15, 0xffff0000, v118
	v_lshlrev_b32_e32 v16, 16, v120
	v_and_b32_e32 v17, 0xffff0000, v120
	v_lshlrev_b32_e32 v18, 16, v119
	v_and_b32_e32 v19, 0xffff0000, v119
	v_lshlrev_b32_e32 v20, 16, v121
	v_and_b32_e32 v21, 0xffff0000, v121
	v_pk_add_f32 v[118:119], v[14:15], v[16:17]
	v_pk_add_f32 v[120:121], v[18:19], v[20:21]
	v_lshlrev_b32_e32 v14, 16, v122
	v_and_b32_e32 v15, 0xffff0000, v122
	v_lshlrev_b32_e32 v16, 16, v124
	v_and_b32_e32 v17, 0xffff0000, v124
	v_lshlrev_b32_e32 v18, 16, v123
	v_and_b32_e32 v19, 0xffff0000, v123
	v_lshlrev_b32_e32 v20, 16, v125
	v_and_b32_e32 v21, 0xffff0000, v125
	v_pk_add_f32 v[122:123], v[14:15], v[16:17]
	v_pk_add_f32 v[124:125], v[18:19], v[20:21]
	v_lshlrev_b32_e32 v14, 16, v134
	v_and_b32_e32 v15, 0xffff0000, v134
	v_lshlrev_b32_e32 v16, 16, v136
	v_and_b32_e32 v17, 0xffff0000, v136
	v_lshlrev_b32_e32 v18, 16, v135
	v_and_b32_e32 v19, 0xffff0000, v135
	v_lshlrev_b32_e32 v20, 16, v137
	v_and_b32_e32 v21, 0xffff0000, v137
	v_pk_add_f32 v[134:135], v[14:15], v[16:17]
	v_pk_add_f32 v[136:137], v[18:19], v[20:21]
	v_lshlrev_b32_e32 v14, 16, v138
	v_and_b32_e32 v15, 0xffff0000, v138
	v_lshlrev_b32_e32 v16, 16, v140
	v_and_b32_e32 v17, 0xffff0000, v140
	v_lshlrev_b32_e32 v18, 16, v139
	v_and_b32_e32 v19, 0xffff0000, v139
	v_lshlrev_b32_e32 v20, 16, v141
	v_and_b32_e32 v21, 0xffff0000, v141
	v_pk_add_f32 v[138:139], v[14:15], v[16:17]
	v_pk_add_f32 v[140:141], v[18:19], v[20:21]
	v_pk_mul_f32 v[12:13], v[118:119], v[118:119]
	v_pk_fma_f32 v[12:13], v[120:121], v[120:121], v[12:13]
	v_pk_fma_f32 v[12:13], v[122:123], v[122:123], v[12:13]
	v_pk_fma_f32 v[12:13], v[124:125], v[124:125], v[12:13]
	v_pk_fma_f32 v[12:13], v[134:135], v[134:135], v[12:13]
	v_pk_fma_f32 v[12:13], v[136:137], v[136:137], v[12:13]
	v_pk_fma_f32 v[12:13], v[138:139], v[138:139], v[12:13]
	v_pk_fma_f32 v[12:13], v[140:141], v[140:141], v[12:13]
	v_add_f32_e32 v5, v12, v13
	s_nop 1
	v_add_f32_dpp v5, v5, v5 quad_perm:[1,0,3,2] row_mask:0xf bank_mask:0xf
	s_nop 1
	v_add_f32_dpp v5, v5, v5 quad_perm:[2,3,0,1] row_mask:0xf bank_mask:0xf
	s_nop 1
	v_add_f32_dpp v5, v5, v5 row_half_mirror row_mask:0xf bank_mask:0xf
	s_nop 1
	v_add_f32_dpp v5, v5, v5 row_mirror row_mask:0xf bank_mask:0xf
	s_nop 1
	v_add_f32_dpp v5, v5, v5 row_bcast:15 row_mask:0xa bank_mask:0xf
	s_nop 1
	v_add_f32_dpp v5, v5, v5 row_bcast:31 row_mask:0xc bank_mask:0xf
	s_nop 1
	v_readlane_b32 s32, v5, 63
	s_nop 1
	v_mov_b32_e32 v6, s32
	v_fmamk_f32 v6, v6, 0x3a800000, v146
	v_rsq_f32_e32 v6, v6
	s_nop 0
	v_mov_b32_e32 v8, v6
	v_pk_mul_f32 v[14:15], v[118:119], v[8:9] op_sel_hi:[1,0]
	v_pk_fma_f32 v[102:103], v[22:23], v[14:15], v[102:103]
	v_pk_mul_f32 v[14:15], v[120:121], v[8:9] op_sel_hi:[1,0]
	v_pk_fma_f32 v[104:105], v[24:25], v[14:15], v[104:105]
	v_pk_mul_f32 v[14:15], v[122:123], v[8:9] op_sel_hi:[1,0]
	v_pk_fma_f32 v[106:107], v[26:27], v[14:15], v[106:107]
	v_pk_mul_f32 v[14:15], v[124:125], v[8:9] op_sel_hi:[1,0]
	v_pk_fma_f32 v[108:109], v[28:29], v[14:15], v[108:109]
	v_pk_mul_f32 v[14:15], v[134:135], v[8:9] op_sel_hi:[1,0]
	v_pk_fma_f32 v[110:111], v[30:31], v[14:15], v[110:111]
	v_pk_mul_f32 v[14:15], v[136:137], v[8:9] op_sel_hi:[1,0]
	v_pk_fma_f32 v[112:113], v[32:33], v[14:15], v[112:113]
	v_pk_mul_f32 v[14:15], v[138:139], v[8:9] op_sel_hi:[1,0]
	v_pk_fma_f32 v[114:115], v[34:35], v[14:15], v[114:115]
	v_pk_mul_f32 v[14:15], v[140:141], v[8:9] op_sel_hi:[1,0]
	v_pk_fma_f32 v[116:117], v[36:37], v[14:15], v[116:117]
	v_pk_mul_f32 v[12:13], v[102:103], v[102:103]
	v_pk_fma_f32 v[12:13], v[104:105], v[104:105], v[12:13]
	v_pk_fma_f32 v[12:13], v[106:107], v[106:107], v[12:13]
	v_pk_fma_f32 v[12:13], v[108:109], v[108:109], v[12:13]
	v_pk_fma_f32 v[12:13], v[110:111], v[110:111], v[12:13]
	v_pk_fma_f32 v[12:13], v[112:113], v[112:113], v[12:13]
	v_pk_fma_f32 v[12:13], v[114:115], v[114:115], v[12:13]
	v_pk_fma_f32 v[12:13], v[116:117], v[116:117], v[12:13]
	v_add_f32_e32 v5, v12, v13
	s_nop 1
	v_add_f32_dpp v5, v5, v5 quad_perm:[1,0,3,2] row_mask:0xf bank_mask:0xf
	s_nop 1
	v_add_f32_dpp v5, v5, v5 quad_perm:[2,3,0,1] row_mask:0xf bank_mask:0xf
	s_nop 1
	v_add_f32_dpp v5, v5, v5 row_half_mirror row_mask:0xf bank_mask:0xf
	s_nop 1
	v_add_f32_dpp v5, v5, v5 row_mirror row_mask:0xf bank_mask:0xf
	s_nop 1
	v_add_f32_dpp v5, v5, v5 row_bcast:15 row_mask:0xa bank_mask:0xf
	s_nop 1
	v_add_f32_dpp v5, v5, v5 row_bcast:31 row_mask:0xc bank_mask:0xf
	s_nop 1
	v_readlane_b32 s32, v5, 63
	s_nop 1
	v_mov_b32_e32 v6, s32
	v_fmamk_f32 v6, v6, 0x3a800000, v146
	v_rsq_f32_e32 v6, v6
	s_nop 0
	v_mov_b32_e32 v10, v6
	v_pk_mul_f32 v[14:15], v[102:103], v[10:11] op_sel_hi:[1,0]
	v_pk_fma_f32 v[16:17], v[54:55], v[14:15], v[38:39]
	v_pk_mul_f32 v[14:15], v[104:105], v[10:11] op_sel_hi:[1,0]
	v_pk_fma_f32 v[18:19], v[56:57], v[14:15], v[40:41]
	v_cvt_pk_bf16_f32 v118, v16, v17
	v_cvt_pk_bf16_f32 v119, v18, v19
	v_pk_mul_f32 v[14:15], v[106:107], v[10:11] op_sel_hi:[1,0]
	v_pk_fma_f32 v[16:17], v[58:59], v[14:15], v[42:43]
	v_pk_mul_f32 v[14:15], v[108:109], v[10:11] op_sel_hi:[1,0]
	v_pk_fma_f32 v[18:19], v[60:61], v[14:15], v[44:45]
	v_cvt_pk_bf16_f32 v122, v16, v17
	v_cvt_pk_bf16_f32 v123, v18, v19
	v_pk_mul_f32 v[14:15], v[110:111], v[10:11] op_sel_hi:[1,0]
	v_pk_fma_f32 v[16:17], v[62:63], v[14:15], v[46:47]
	v_pk_mul_f32 v[14:15], v[112:113], v[10:11] op_sel_hi:[1,0]
	v_pk_fma_f32 v[18:19], v[64:65], v[14:15], v[48:49]
	v_cvt_pk_bf16_f32 v134, v16, v17
	v_cvt_pk_bf16_f32 v135, v18, v19
	v_pk_mul_f32 v[14:15], v[114:115], v[10:11] op_sel_hi:[1,0]
	v_pk_fma_f32 v[16:17], v[66:67], v[14:15], v[50:51]
	v_pk_mul_f32 v[14:15], v[116:117], v[10:11] op_sel_hi:[1,0]
	v_pk_fma_f32 v[18:19], v[68:69], v[14:15], v[52:53]
	v_cvt_pk_bf16_f32 v138, v16, v17
	v_cvt_pk_bf16_f32 v139, v18, v19
	global_store_dwordx2 v1, v[118:119], s[62:63] offset:0
	global_store_dwordx2 v1, v[122:123], s[62:63] offset:512
	global_store_dwordx2 v1, v[134:135], s[62:63] offset:1024
	global_store_dwordx2 v1, v[138:139], s[62:63] offset:1536
	global_store_dwordx4 v0, v[102:105], s[46:47] offset:0
	global_store_dwordx4 v0, v[106:109], s[46:47] offset:1024
	global_store_dwordx4 v0, v[110:113], s[46:47] offset:2048
	global_store_dwordx4 v0, v[114:117], s[46:47] offset:3072
	s_add_u32 s46, s46, 0x1000
	s_addc_u32 s47, s47, 0
	s_add_u32 s62, s62, 0x800
	s_addc_u32 s63, s63, 0
	s_waitcnt vmcnt(24)
	v_lshlrev_b32_e32 v14, 16, v172
	v_and_b32_e32 v15, 0xffff0000, v172
	v_lshlrev_b32_e32 v16, 16, v174
	v_and_b32_e32 v17, 0xffff0000, v174
	v_lshlrev_b32_e32 v18, 16, v173
	v_and_b32_e32 v19, 0xffff0000, v173
	v_lshlrev_b32_e32 v20, 16, v175
	v_and_b32_e32 v21, 0xffff0000, v175
	v_pk_add_f32 v[172:173], v[14:15], v[16:17]
	v_pk_add_f32 v[174:175], v[18:19], v[20:21]
	v_lshlrev_b32_e32 v14, 16, v176
	v_and_b32_e32 v15, 0xffff0000, v176
	v_lshlrev_b32_e32 v16, 16, v178
	v_and_b32_e32 v17, 0xffff0000, v178
	v_lshlrev_b32_e32 v18, 16, v177
	v_and_b32_e32 v19, 0xffff0000, v177
	v_lshlrev_b32_e32 v20, 16, v179
	v_and_b32_e32 v21, 0xffff0000, v179
	v_pk_add_f32 v[176:177], v[14:15], v[16:17]
	v_pk_add_f32 v[178:179], v[18:19], v[20:21]
	v_lshlrev_b32_e32 v14, 16, v204
	v_and_b32_e32 v15, 0xffff0000, v204
	v_lshlrev_b32_e32 v16, 16, v206
	v_and_b32_e32 v17, 0xffff0000, v206
	v_lshlrev_b32_e32 v18, 16, v205
	v_and_b32_e32 v19, 0xffff0000, v205
	v_lshlrev_b32_e32 v20, 16, v207
	v_and_b32_e32 v21, 0xffff0000, v207
	v_pk_add_f32 v[204:205], v[14:15], v[16:17]
	v_pk_add_f32 v[206:207], v[18:19], v[20:21]
	v_lshlrev_b32_e32 v14, 16, v214
	v_and_b32_e32 v15, 0xffff0000, v214
	v_lshlrev_b32_e32 v16, 16, v216
	v_and_b32_e32 v17, 0xffff0000, v216
	v_lshlrev_b32_e32 v18, 16, v215
	v_and_b32_e32 v19, 0xffff0000, v215
	v_lshlrev_b32_e32 v20, 16, v217
	v_and_b32_e32 v21, 0xffff0000, v217
	v_pk_add_f32 v[214:215], v[14:15], v[16:17]
	v_pk_add_f32 v[216:217], v[18:19], v[20:21]
	v_pk_mul_f32 v[12:13], v[172:173], v[172:173]
	v_pk_fma_f32 v[12:13], v[174:175], v[174:175], v[12:13]
	v_pk_fma_f32 v[12:13], v[176:177], v[176:177], v[12:13]
	v_pk_fma_f32 v[12:13], v[178:179], v[178:179], v[12:13]
	v_pk_fma_f32 v[12:13], v[204:205], v[204:205], v[12:13]
	v_pk_fma_f32 v[12:13], v[206:207], v[206:207], v[12:13]
	v_pk_fma_f32 v[12:13], v[214:215], v[214:215], v[12:13]
	v_pk_fma_f32 v[12:13], v[216:217], v[216:217], v[12:13]
	v_add_f32_e32 v5, v12, v13
	s_nop 1
	v_add_f32_dpp v5, v5, v5 quad_perm:[1,0,3,2] row_mask:0xf bank_mask:0xf
	s_nop 1
	v_add_f32_dpp v5, v5, v5 quad_perm:[2,3,0,1] row_mask:0xf bank_mask:0xf
	s_nop 1
	v_add_f32_dpp v5, v5, v5 row_half_mirror row_mask:0xf bank_mask:0xf
	s_nop 1
	v_add_f32_dpp v5, v5, v5 row_mirror row_mask:0xf bank_mask:0xf
	s_nop 1
	v_add_f32_dpp v5, v5, v5 row_bcast:15 row_mask:0xa bank_mask:0xf
	s_nop 1
	v_add_f32_dpp v5, v5, v5 row_bcast:31 row_mask:0xc bank_mask:0xf
	s_nop 1
	v_readlane_b32 s32, v5, 63
	s_nop 1
	v_mov_b32_e32 v6, s32
	v_fmamk_f32 v6, v6, 0x3a800000, v146
	v_rsq_f32_e32 v6, v6
	s_nop 0
	v_mov_b32_e32 v8, v6
	v_pk_mul_f32 v[14:15], v[172:173], v[8:9] op_sel_hi:[1,0]
	v_pk_fma_f32 v[154:155], v[22:23], v[14:15], v[154:155]
	v_pk_mul_f32 v[14:15], v[174:175], v[8:9] op_sel_hi:[1,0]
	v_pk_fma_f32 v[156:157], v[24:25], v[14:15], v[156:157]
	v_pk_mul_f32 v[14:15], v[176:177], v[8:9] op_sel_hi:[1,0]
	v_pk_fma_f32 v[158:159], v[26:27], v[14:15], v[158:159]
	v_pk_mul_f32 v[14:15], v[178:179], v[8:9] op_sel_hi:[1,0]
	v_pk_fma_f32 v[160:161], v[28:29], v[14:15], v[160:161]
	v_pk_mul_f32 v[14:15], v[204:205], v[8:9] op_sel_hi:[1,0]
	v_pk_fma_f32 v[162:163], v[30:31], v[14:15], v[162:163]
	v_pk_mul_f32 v[14:15], v[206:207], v[8:9] op_sel_hi:[1,0]
	v_pk_fma_f32 v[164:165], v[32:33], v[14:15], v[164:165]
	v_pk_mul_f32 v[14:15], v[214:215], v[8:9] op_sel_hi:[1,0]
	v_pk_fma_f32 v[168:169], v[34:35], v[14:15], v[168:169]
	v_pk_mul_f32 v[14:15], v[216:217], v[8:9] op_sel_hi:[1,0]
	v_pk_fma_f32 v[170:171], v[36:37], v[14:15], v[170:171]
	v_pk_mul_f32 v[12:13], v[154:155], v[154:155]
	v_pk_fma_f32 v[12:13], v[156:157], v[156:157], v[12:13]
	v_pk_fma_f32 v[12:13], v[158:159], v[158:159], v[12:13]
	v_pk_fma_f32 v[12:13], v[160:161], v[160:161], v[12:13]
	v_pk_fma_f32 v[12:13], v[162:163], v[162:163], v[12:13]
	v_pk_fma_f32 v[12:13], v[164:165], v[164:165], v[12:13]
	v_pk_fma_f32 v[12:13], v[168:169], v[168:169], v[12:13]
	v_pk_fma_f32 v[12:13], v[170:171], v[170:171], v[12:13]
	v_add_f32_e32 v5, v12, v13
	s_nop 1
	v_add_f32_dpp v5, v5, v5 quad_perm:[1,0,3,2] row_mask:0xf bank_mask:0xf
	s_nop 1
	v_add_f32_dpp v5, v5, v5 quad_perm:[2,3,0,1] row_mask:0xf bank_mask:0xf
	s_nop 1
	v_add_f32_dpp v5, v5, v5 row_half_mirror row_mask:0xf bank_mask:0xf
	s_nop 1
	v_add_f32_dpp v5, v5, v5 row_mirror row_mask:0xf bank_mask:0xf
	s_nop 1
	v_add_f32_dpp v5, v5, v5 row_bcast:15 row_mask:0xa bank_mask:0xf
	s_nop 1
	v_add_f32_dpp v5, v5, v5 row_bcast:31 row_mask:0xc bank_mask:0xf
	s_nop 1
	v_readlane_b32 s32, v5, 63
	s_nop 1
	v_mov_b32_e32 v6, s32
	v_fmamk_f32 v6, v6, 0x3a800000, v146
	v_rsq_f32_e32 v6, v6
	s_nop 0
	v_mov_b32_e32 v10, v6
	v_pk_mul_f32 v[14:15], v[154:155], v[10:11] op_sel_hi:[1,0]
	v_pk_fma_f32 v[16:17], v[54:55], v[14:15], v[38:39]
	v_pk_mul_f32 v[14:15], v[156:157], v[10:11] op_sel_hi:[1,0]
	v_pk_fma_f32 v[18:19], v[56:57], v[14:15], v[40:41]
	v_cvt_pk_bf16_f32 v172, v16, v17
	v_cvt_pk_bf16_f32 v173, v18, v19
	v_pk_mul_f32 v[14:15], v[158:159], v[10:11] op_sel_hi:[1,0]
	v_pk_fma_f32 v[16:17], v[58:59], v[14:15], v[42:43]
	v_pk_mul_f32 v[14:15], v[160:161], v[10:11] op_sel_hi:[1,0]
	v_pk_fma_f32 v[18:19], v[60:61], v[14:15], v[44:45]
	v_cvt_pk_bf16_f32 v176, v16, v17
	v_cvt_pk_bf16_f32 v177, v18, v19
	v_pk_mul_f32 v[14:15], v[162:163], v[10:11] op_sel_hi:[1,0]
	v_pk_fma_f32 v[16:17], v[62:63], v[14:15], v[46:47]
	v_pk_mul_f32 v[14:15], v[164:165], v[10:11] op_sel_hi:[1,0]
	v_pk_fma_f32 v[18:19], v[64:65], v[14:15], v[48:49]
	v_cvt_pk_bf16_f32 v204, v16, v17
	v_cvt_pk_bf16_f32 v205, v18, v19
	v_pk_mul_f32 v[14:15], v[168:169], v[10:11] op_sel_hi:[1,0]
	v_pk_fma_f32 v[16:17], v[66:67], v[14:15], v[50:51]
	v_pk_mul_f32 v[14:15], v[170:171], v[10:11] op_sel_hi:[1,0]
	v_pk_fma_f32 v[18:19], v[68:69], v[14:15], v[52:53]
	v_cvt_pk_bf16_f32 v214, v16, v17
	v_cvt_pk_bf16_f32 v215, v18, v19
	global_store_dwordx2 v1, v[172:173], s[62:63] offset:0
	global_store_dwordx2 v1, v[176:177], s[62:63] offset:512
	global_store_dwordx2 v1, v[204:205], s[62:63] offset:1024
	global_store_dwordx2 v1, v[214:215], s[62:63] offset:1536
	global_store_dwordx4 v0, v[154:157], s[46:47] offset:0
	global_store_dwordx4 v0, v[158:161], s[46:47] offset:1024
	global_store_dwordx4 v0, v[162:165], s[46:47] offset:2048
	global_store_dwordx4 v0, v[168:171], s[46:47] offset:3072
	s_add_u32 s46, s46, 0x1000
	s_addc_u32 s47, s47, 0
	s_add_u32 s62, s62, 0x800
	s_addc_u32 s63, s63, 0
	s_waitcnt vmcnt(24)
	v_lshlrev_b32_e32 v14, 16, v234
	v_and_b32_e32 v15, 0xffff0000, v234
	v_lshlrev_b32_e32 v16, 16, v236
	v_and_b32_e32 v17, 0xffff0000, v236
	v_lshlrev_b32_e32 v18, 16, v235
	v_and_b32_e32 v19, 0xffff0000, v235
	v_lshlrev_b32_e32 v20, 16, v237
	v_and_b32_e32 v21, 0xffff0000, v237
	v_pk_add_f32 v[234:235], v[14:15], v[16:17]
	v_pk_add_f32 v[236:237], v[18:19], v[20:21]
	v_lshlrev_b32_e32 v14, 16, v238
	v_and_b32_e32 v15, 0xffff0000, v238
	v_lshlrev_b32_e32 v16, 16, v240
	v_and_b32_e32 v17, 0xffff0000, v240
	v_lshlrev_b32_e32 v18, 16, v239
	v_and_b32_e32 v19, 0xffff0000, v239
	v_lshlrev_b32_e32 v20, 16, v241
	v_and_b32_e32 v21, 0xffff0000, v241
	v_pk_add_f32 v[238:239], v[14:15], v[16:17]
	v_pk_add_f32 v[240:241], v[18:19], v[20:21]
	v_lshlrev_b32_e32 v14, 16, v242
	v_and_b32_e32 v15, 0xffff0000, v242
	v_lshlrev_b32_e32 v16, 16, v244
	v_and_b32_e32 v17, 0xffff0000, v244
	v_lshlrev_b32_e32 v18, 16, v243
	v_and_b32_e32 v19, 0xffff0000, v243
	v_lshlrev_b32_e32 v20, 16, v245
	v_and_b32_e32 v21, 0xffff0000, v245
	v_pk_add_f32 v[242:243], v[14:15], v[16:17]
	v_pk_add_f32 v[244:245], v[18:19], v[20:21]
	v_lshlrev_b32_e32 v14, 16, v246
	v_and_b32_e32 v15, 0xffff0000, v246
	v_lshlrev_b32_e32 v16, 16, v248
	v_and_b32_e32 v17, 0xffff0000, v248
	v_lshlrev_b32_e32 v18, 16, v247
	v_and_b32_e32 v19, 0xffff0000, v247
	v_lshlrev_b32_e32 v20, 16, v249
	v_and_b32_e32 v21, 0xffff0000, v249
	v_pk_add_f32 v[246:247], v[14:15], v[16:17]
	v_pk_add_f32 v[248:249], v[18:19], v[20:21]
	v_pk_mul_f32 v[12:13], v[234:235], v[234:235]
	v_pk_fma_f32 v[12:13], v[236:237], v[236:237], v[12:13]
	v_pk_fma_f32 v[12:13], v[238:239], v[238:239], v[12:13]
	v_pk_fma_f32 v[12:13], v[240:241], v[240:241], v[12:13]
	v_pk_fma_f32 v[12:13], v[242:243], v[242:243], v[12:13]
	v_pk_fma_f32 v[12:13], v[244:245], v[244:245], v[12:13]
	v_pk_fma_f32 v[12:13], v[246:247], v[246:247], v[12:13]
	v_pk_fma_f32 v[12:13], v[248:249], v[248:249], v[12:13]
	v_add_f32_e32 v5, v12, v13
	s_nop 1
	v_add_f32_dpp v5, v5, v5 quad_perm:[1,0,3,2] row_mask:0xf bank_mask:0xf
	s_nop 1
	v_add_f32_dpp v5, v5, v5 quad_perm:[2,3,0,1] row_mask:0xf bank_mask:0xf
	s_nop 1
	v_add_f32_dpp v5, v5, v5 row_half_mirror row_mask:0xf bank_mask:0xf
	s_nop 1
	v_add_f32_dpp v5, v5, v5 row_mirror row_mask:0xf bank_mask:0xf
	s_nop 1
	v_add_f32_dpp v5, v5, v5 row_bcast:15 row_mask:0xa bank_mask:0xf
	s_nop 1
	v_add_f32_dpp v5, v5, v5 row_bcast:31 row_mask:0xc bank_mask:0xf
	s_nop 1
	v_readlane_b32 s32, v5, 63
	s_nop 1
	v_mov_b32_e32 v6, s32
	v_fmamk_f32 v6, v6, 0x3a800000, v146
	v_rsq_f32_e32 v6, v6
	s_nop 0
	v_mov_b32_e32 v8, v6
	v_pk_mul_f32 v[14:15], v[234:235], v[8:9] op_sel_hi:[1,0]
	v_pk_fma_f32 v[218:219], v[22:23], v[14:15], v[218:219]
	v_pk_mul_f32 v[14:15], v[236:237], v[8:9] op_sel_hi:[1,0]
	v_pk_fma_f32 v[220:221], v[24:25], v[14:15], v[220:221]
	v_pk_mul_f32 v[14:15], v[238:239], v[8:9] op_sel_hi:[1,0]
	v_pk_fma_f32 v[222:223], v[26:27], v[14:15], v[222:223]
	v_pk_mul_f32 v[14:15], v[240:241], v[8:9] op_sel_hi:[1,0]
	v_pk_fma_f32 v[224:225], v[28:29], v[14:15], v[224:225]
	v_pk_mul_f32 v[14:15], v[242:243], v[8:9] op_sel_hi:[1,0]
	v_pk_fma_f32 v[226:227], v[30:31], v[14:15], v[226:227]
	v_pk_mul_f32 v[14:15], v[244:245], v[8:9] op_sel_hi:[1,0]
	v_pk_fma_f32 v[228:229], v[32:33], v[14:15], v[228:229]
	v_pk_mul_f32 v[14:15], v[246:247], v[8:9] op_sel_hi:[1,0]
	v_pk_fma_f32 v[230:231], v[34:35], v[14:15], v[230:231]
	v_pk_mul_f32 v[14:15], v[248:249], v[8:9] op_sel_hi:[1,0]
	v_pk_fma_f32 v[232:233], v[36:37], v[14:15], v[232:233]
	v_pk_mul_f32 v[12:13], v[218:219], v[218:219]
	v_pk_fma_f32 v[12:13], v[220:221], v[220:221], v[12:13]
	v_pk_fma_f32 v[12:13], v[222:223], v[222:223], v[12:13]
	v_pk_fma_f32 v[12:13], v[224:225], v[224:225], v[12:13]
	v_pk_fma_f32 v[12:13], v[226:227], v[226:227], v[12:13]
	v_pk_fma_f32 v[12:13], v[228:229], v[228:229], v[12:13]
	v_pk_fma_f32 v[12:13], v[230:231], v[230:231], v[12:13]
	v_pk_fma_f32 v[12:13], v[232:233], v[232:233], v[12:13]
	v_add_f32_e32 v5, v12, v13
	s_nop 1
	v_add_f32_dpp v5, v5, v5 quad_perm:[1,0,3,2] row_mask:0xf bank_mask:0xf
	s_nop 1
	v_add_f32_dpp v5, v5, v5 quad_perm:[2,3,0,1] row_mask:0xf bank_mask:0xf
	s_nop 1
	v_add_f32_dpp v5, v5, v5 row_half_mirror row_mask:0xf bank_mask:0xf
	s_nop 1
	v_add_f32_dpp v5, v5, v5 row_mirror row_mask:0xf bank_mask:0xf
	s_nop 1
	v_add_f32_dpp v5, v5, v5 row_bcast:15 row_mask:0xa bank_mask:0xf
	s_nop 1
	v_add_f32_dpp v5, v5, v5 row_bcast:31 row_mask:0xc bank_mask:0xf
	s_nop 1
	v_readlane_b32 s32, v5, 63
	s_nop 1
	v_mov_b32_e32 v6, s32
	v_fmamk_f32 v6, v6, 0x3a800000, v146
	v_rsq_f32_e32 v6, v6
	s_nop 0
	v_mov_b32_e32 v10, v6
	v_pk_mul_f32 v[14:15], v[218:219], v[10:11] op_sel_hi:[1,0]
	v_pk_fma_f32 v[16:17], v[54:55], v[14:15], v[38:39]
	v_pk_mul_f32 v[14:15], v[220:221], v[10:11] op_sel_hi:[1,0]
	v_pk_fma_f32 v[18:19], v[56:57], v[14:15], v[40:41]
	v_cvt_pk_bf16_f32 v234, v16, v17
	v_cvt_pk_bf16_f32 v235, v18, v19
	v_pk_mul_f32 v[14:15], v[222:223], v[10:11] op_sel_hi:[1,0]
	v_pk_fma_f32 v[16:17], v[58:59], v[14:15], v[42:43]
	v_pk_mul_f32 v[14:15], v[224:225], v[10:11] op_sel_hi:[1,0]
	v_pk_fma_f32 v[18:19], v[60:61], v[14:15], v[44:45]
	v_cvt_pk_bf16_f32 v238, v16, v17
	v_cvt_pk_bf16_f32 v239, v18, v19
	v_pk_mul_f32 v[14:15], v[226:227], v[10:11] op_sel_hi:[1,0]
	v_pk_fma_f32 v[16:17], v[62:63], v[14:15], v[46:47]
	v_pk_mul_f32 v[14:15], v[228:229], v[10:11] op_sel_hi:[1,0]
	v_pk_fma_f32 v[18:19], v[64:65], v[14:15], v[48:49]
	v_cvt_pk_bf16_f32 v242, v16, v17
	v_cvt_pk_bf16_f32 v243, v18, v19
	v_pk_mul_f32 v[14:15], v[230:231], v[10:11] op_sel_hi:[1,0]
	v_pk_fma_f32 v[16:17], v[66:67], v[14:15], v[50:51]
	v_pk_mul_f32 v[14:15], v[232:233], v[10:11] op_sel_hi:[1,0]
	v_pk_fma_f32 v[18:19], v[68:69], v[14:15], v[52:53]
	v_cvt_pk_bf16_f32 v246, v16, v17
	v_cvt_pk_bf16_f32 v247, v18, v19
	global_store_dwordx2 v1, v[234:235], s[62:63] offset:0
	global_store_dwordx2 v1, v[238:239], s[62:63] offset:512
	global_store_dwordx2 v1, v[242:243], s[62:63] offset:1024
	global_store_dwordx2 v1, v[246:247], s[62:63] offset:1536
	global_store_dwordx4 v0, v[218:221], s[46:47] offset:0
	global_store_dwordx4 v0, v[222:225], s[46:47] offset:1024
	global_store_dwordx4 v0, v[226:229], s[46:47] offset:2048
	global_store_dwordx4 v0, v[230:233], s[46:47] offset:3072
	s_add_u32 s46, s46, 0x1000
	s_addc_u32 s47, s47, 0
	s_add_u32 s62, s62, 0x800
	s_addc_u32 s63, s63, 0
